# speedup vs baseline: 1.0152x; 1.0035x over previous
.LBB0_377:
	s_add_u32 s3, s16, 0xfff80080
	s_addc_u32 s18, s17, -1
	s_add_i32 s42, 0, 0x10000
	s_cmp_eq_u32 s41, 28
	s_cselect_b32 s21, s11, s18
	s_cselect_b32 s20, s31, s3
	v_add_u32_e32 v152, s42, v155
	s_cselect_b32 s19, s9, s40
	s_cselect_b32 s18, s34, s35
	s_add_i32 s3, 0, 0x14000
	ds_read_b128 v[140:143], v152
	ds_read_b128 v[144:147], v152 offset:1024
	ds_read_b128 v[148:151], v152 offset:2048
	ds_read_b128 v[158:161], v152 offset:3072
	v_add_u32_e32 v152, s3, v155
	ds_read_b128 v[162:165], v152
	ds_read_b128 v[166:169], v152 offset:1024
	ds_read_b128 v[170:173], v152 offset:2048
	ds_read_b128 v[174:177], v152 offset:3072
	v_lshl_add_u64 v[152:153], s[16:17], 0, v[136:137]
	s_add_i32 m0, s22, 0xc000
	ds_read_b128 v[188:191], v157
	ds_read_b128 v[192:195], v157 offset:1024
	ds_read_b128 v[196:199], v157 offset:2048
	ds_read_b128 v[200:203], v157 offset:3072
	ds_read_b128 v[204:207], v157 offset:4096
	ds_read_b128 v[218:221], v157 offset:5120
	ds_read_b128 v[222:225], v157 offset:6144
	ds_read_b128 v[226:229], v157 offset:7168
	global_load_lds_dwordx4 v[152:153], off
	v_lshl_add_u64 v[152:153], s[16:17], 0, v[138:139]
	s_add_i32 m0, s22, 0xe000
	s_nop 0
	global_load_lds_dwordx4 v[152:153], off
	s_waitcnt vmcnt(8)
	s_waitcnt lgkmcnt(0)
	s_waitcnt lgkmcnt(0)
	v_mfma_f32_16x16x32_bf16 v[126:129], v[140:143], v[188:191], v[126:129]
	v_mfma_f32_16x16x32_bf16 v[122:125], v[148:151], v[188:191], v[122:125]
	s_barrier
	s_setprio 1
	v_mfma_f32_16x16x32_bf16 v[110:113], v[140:143], v[196:199], v[110:113]
	v_mfma_f32_16x16x32_bf16 v[106:109], v[148:151], v[196:199], v[106:109]
	v_mfma_f32_16x16x32_bf16 v[94:97], v[140:143], v[204:207], v[94:97]
	v_mfma_f32_16x16x32_bf16 v[90:93], v[148:151], v[204:207], v[90:93]
	v_mfma_f32_16x16x32_bf16 v[78:81], v[140:143], v[222:225], v[78:81]
	v_mfma_f32_16x16x32_bf16 v[74:77], v[148:151], v[222:225], v[74:77]
	v_mfma_f32_16x16x32_bf16 v[126:129], v[144:147], v[192:195], v[126:129]
	v_mfma_f32_16x16x32_bf16 v[122:125], v[158:161], v[192:195], v[122:125]
	v_mfma_f32_16x16x32_bf16 v[110:113], v[144:147], v[200:203], v[110:113]
	v_mfma_f32_16x16x32_bf16 v[106:109], v[158:161], v[200:203], v[106:109]
	v_mfma_f32_16x16x32_bf16 v[94:97], v[144:147], v[218:221], v[94:97]
	v_mfma_f32_16x16x32_bf16 v[90:93], v[158:161], v[218:221], v[90:93]
	v_mfma_f32_16x16x32_bf16 v[78:81], v[144:147], v[226:229], v[78:81]
	v_mfma_f32_16x16x32_bf16 v[74:77], v[158:161], v[226:229], v[74:77]
	s_setprio 0
	s_setprio 1
	v_mfma_f32_16x16x32_bf16 v[118:121], v[162:165], v[188:191], v[118:121]
	v_mfma_f32_16x16x32_bf16 v[114:117], v[170:173], v[188:191], v[114:117]
	v_mfma_f32_16x16x32_bf16 v[102:105], v[162:165], v[196:199], v[102:105]
	v_mfma_f32_16x16x32_bf16 v[98:101], v[170:173], v[196:199], v[98:101]
	v_mfma_f32_16x16x32_bf16 v[86:89], v[162:165], v[204:207], v[86:89]
	v_mfma_f32_16x16x32_bf16 v[82:85], v[170:173], v[204:207], v[82:85]
	v_mfma_f32_16x16x32_bf16 v[70:73], v[162:165], v[222:225], v[70:73]
	v_mfma_f32_16x16x32_bf16 v[66:69], v[170:173], v[222:225], v[66:69]
	v_mfma_f32_16x16x32_bf16 v[118:121], v[166:169], v[192:195], v[118:121]
	v_mfma_f32_16x16x32_bf16 v[114:117], v[174:177], v[192:195], v[114:117]
	v_mfma_f32_16x16x32_bf16 v[102:105], v[166:169], v[200:203], v[102:105]
	v_mfma_f32_16x16x32_bf16 v[98:101], v[174:177], v[200:203], v[98:101]
	v_mfma_f32_16x16x32_bf16 v[86:89], v[166:169], v[218:221], v[86:89]
	v_mfma_f32_16x16x32_bf16 v[82:85], v[174:177], v[218:221], v[82:85]
	v_mfma_f32_16x16x32_bf16 v[70:73], v[166:169], v[226:229], v[70:73]
	v_mfma_f32_16x16x32_bf16 v[66:69], v[174:177], v[226:229], v[66:69]
	s_setprio 0
	s_barrier
	s_add_i32 s42, s42, s2
	v_lshl_add_u64 v[152:153], s[18:19], 0, v[0:1]
	s_mov_b32 m0, s42
	ds_read_b128 v[188:191], v157 offset:16384
	ds_read_b128 v[192:195], v157 offset:17408
	ds_read_b128 v[196:199], v157 offset:18432
	ds_read_b128 v[200:203], v157 offset:19456
	ds_read_b128 v[204:207], v157 offset:20480
	ds_read_b128 v[218:221], v157 offset:21504
	ds_read_b128 v[222:225], v157 offset:22528
	ds_read_b128 v[226:229], v157 offset:23552
	global_load_lds_dwordx4 v[152:153], off
	s_add_i32 m0, s42, 0x2000
	s_add_u32 s44, s18, 0x80000
	v_lshl_add_u64 v[178:179], s[18:19], 0, v[130:131]
	s_addc_u32 s45, s19, 0
	s_add_i32 s3, s3, s2
	global_load_lds_dwordx4 v[178:179], off
	v_lshl_add_u64 v[180:181], s[44:45], 0, v[0:1]
	s_mov_b32 m0, s3
	v_lshl_add_u64 v[182:183], s[20:21], 0, v[132:133]
	global_load_lds_dwordx4 v[180:181], off
	v_lshl_add_u64 v[180:181], s[44:45], 0, v[130:131]
	s_add_i32 m0, s3, 0x2000
	s_nop 0
	global_load_lds_dwordx4 v[180:181], off
	v_lshl_add_u64 v[180:181], s[20:21], 0, v[134:135]
	s_mov_b32 m0, s22
	s_nop 0
	global_load_lds_dwordx4 v[180:181], off
	s_mov_b32 m0, s23
	s_nop 0
	global_load_lds_dwordx4 v[182:183], off
	s_waitcnt vmcnt(8)
	s_waitcnt lgkmcnt(0)
	s_waitcnt lgkmcnt(0)
	v_mfma_f32_16x16x32_bf16 v[62:65], v[140:143], v[188:191], v[62:65]
	v_mfma_f32_16x16x32_bf16 v[58:61], v[148:151], v[188:191], v[58:61]
	s_barrier
	s_setprio 1
	v_mfma_f32_16x16x32_bf16 v[46:49], v[140:143], v[196:199], v[46:49]
	v_mfma_f32_16x16x32_bf16 v[42:45], v[148:151], v[196:199], v[42:45]
	v_mfma_f32_16x16x32_bf16 v[30:33], v[140:143], v[204:207], v[30:33]
	v_mfma_f32_16x16x32_bf16 v[26:29], v[148:151], v[204:207], v[26:29]
	v_mfma_f32_16x16x32_bf16 v[14:17], v[140:143], v[222:225], v[14:17]
	v_mfma_f32_16x16x32_bf16 v[6:9], v[148:151], v[222:225], v[6:9]
	v_mfma_f32_16x16x32_bf16 v[62:65], v[144:147], v[192:195], v[62:65]
	v_mfma_f32_16x16x32_bf16 v[58:61], v[158:161], v[192:195], v[58:61]
	v_mfma_f32_16x16x32_bf16 v[46:49], v[144:147], v[200:203], v[46:49]
	v_mfma_f32_16x16x32_bf16 v[42:45], v[158:161], v[200:203], v[42:45]
	v_mfma_f32_16x16x32_bf16 v[30:33], v[144:147], v[218:221], v[30:33]
	v_mfma_f32_16x16x32_bf16 v[26:29], v[158:161], v[218:221], v[26:29]
	v_mfma_f32_16x16x32_bf16 v[14:17], v[144:147], v[226:229], v[14:17]
	v_mfma_f32_16x16x32_bf16 v[6:9], v[158:161], v[226:229], v[6:9]
	s_setprio 0
	s_setprio 1
	v_mfma_f32_16x16x32_bf16 v[54:57], v[162:165], v[188:191], v[54:57]
	v_mfma_f32_16x16x32_bf16 v[50:53], v[170:173], v[188:191], v[50:53]
	v_mfma_f32_16x16x32_bf16 v[38:41], v[162:165], v[196:199], v[38:41]
	v_mfma_f32_16x16x32_bf16 v[34:37], v[170:173], v[196:199], v[34:37]
	v_mfma_f32_16x16x32_bf16 v[22:25], v[162:165], v[204:207], v[22:25]
	v_mfma_f32_16x16x32_bf16 v[18:21], v[170:173], v[204:207], v[18:21]
	v_mfma_f32_16x16x32_bf16 v[10:13], v[162:165], v[222:225], v[10:13]
	v_mfma_f32_16x16x32_bf16 v[2:5], v[170:173], v[222:225], v[2:5]
	v_mfma_f32_16x16x32_bf16 v[54:57], v[166:169], v[192:195], v[54:57]
	v_mfma_f32_16x16x32_bf16 v[50:53], v[174:177], v[192:195], v[50:53]
	v_mfma_f32_16x16x32_bf16 v[38:41], v[166:169], v[200:203], v[38:41]
	v_mfma_f32_16x16x32_bf16 v[34:37], v[174:177], v[200:203], v[34:37]
	v_mfma_f32_16x16x32_bf16 v[22:25], v[166:169], v[218:221], v[22:25]
	v_mfma_f32_16x16x32_bf16 v[18:21], v[174:177], v[218:221], v[18:21]
	v_mfma_f32_16x16x32_bf16 v[10:13], v[166:169], v[226:229], v[10:13]
	v_mfma_f32_16x16x32_bf16 v[2:5], v[174:177], v[226:229], v[2:5]
	s_setprio 0
	s_barrier
	s_add_i32 s3, 0, 0x18000
	s_add_i32 s42, 0, 0x1c000
	v_add_u32_e32 v158, s3, v155
	v_add_u32_e32 v174, s42, v155
	ds_read_b128 v[140:143], v158
	ds_read_b128 v[144:147], v158 offset:1024
	ds_read_b128 v[148:151], v158 offset:2048
	ds_read_b128 v[158:161], v158 offset:3072
	ds_read_b128 v[162:165], v174
	ds_read_b128 v[166:169], v174 offset:1024
	ds_read_b128 v[170:173], v174 offset:2048
	ds_read_b128 v[174:177], v174 offset:3072
	s_add_u32 s20, s20, 0x80000
	s_addc_u32 s21, s21, 0
	s_mov_b32 m0, s24
	v_lshl_add_u64 v[184:185], s[20:21], 0, v[134:135]
	ds_read_b128 v[188:191], v157 offset:32768
	ds_read_b128 v[192:195], v157 offset:33792
	ds_read_b128 v[196:199], v157 offset:34816
	ds_read_b128 v[200:203], v157 offset:35840
	ds_read_b128 v[204:207], v157 offset:36864
	ds_read_b128 v[218:221], v157 offset:37888
	ds_read_b128 v[222:225], v157 offset:38912
	ds_read_b128 v[226:229], v157 offset:39936
	global_load_lds_dwordx4 v[184:185], off
	v_lshl_add_u64 v[184:185], s[20:21], 0, v[132:133]
	s_mov_b32 m0, s25
	s_nop 0
	global_load_lds_dwordx4 v[184:185], off
	s_waitcnt vmcnt(8)
	s_waitcnt lgkmcnt(0)
	s_waitcnt lgkmcnt(0)
	v_mfma_f32_16x16x32_bf16 v[126:129], v[140:143], v[188:191], v[126:129]
	v_mfma_f32_16x16x32_bf16 v[122:125], v[148:151], v[188:191], v[122:125]
	s_barrier
	s_setprio 1
	v_mfma_f32_16x16x32_bf16 v[110:113], v[140:143], v[196:199], v[110:113]
	v_mfma_f32_16x16x32_bf16 v[106:109], v[148:151], v[196:199], v[106:109]
	v_mfma_f32_16x16x32_bf16 v[94:97], v[140:143], v[204:207], v[94:97]
	v_mfma_f32_16x16x32_bf16 v[90:93], v[148:151], v[204:207], v[90:93]
	v_mfma_f32_16x16x32_bf16 v[78:81], v[140:143], v[222:225], v[78:81]
	v_mfma_f32_16x16x32_bf16 v[74:77], v[148:151], v[222:225], v[74:77]
	v_mfma_f32_16x16x32_bf16 v[126:129], v[144:147], v[192:195], v[126:129]
	v_mfma_f32_16x16x32_bf16 v[122:125], v[158:161], v[192:195], v[122:125]
	v_mfma_f32_16x16x32_bf16 v[110:113], v[144:147], v[200:203], v[110:113]
	v_mfma_f32_16x16x32_bf16 v[106:109], v[158:161], v[200:203], v[106:109]
	v_mfma_f32_16x16x32_bf16 v[94:97], v[144:147], v[218:221], v[94:97]
	v_mfma_f32_16x16x32_bf16 v[90:93], v[158:161], v[218:221], v[90:93]
	v_mfma_f32_16x16x32_bf16 v[78:81], v[144:147], v[226:229], v[78:81]
	v_mfma_f32_16x16x32_bf16 v[74:77], v[158:161], v[226:229], v[74:77]
	s_setprio 0
	s_setprio 1
	v_mfma_f32_16x16x32_bf16 v[118:121], v[162:165], v[188:191], v[118:121]
	v_mfma_f32_16x16x32_bf16 v[114:117], v[170:173], v[188:191], v[114:117]
	v_mfma_f32_16x16x32_bf16 v[102:105], v[162:165], v[196:199], v[102:105]
	v_mfma_f32_16x16x32_bf16 v[98:101], v[170:173], v[196:199], v[98:101]
	v_mfma_f32_16x16x32_bf16 v[86:89], v[162:165], v[204:207], v[86:89]
	v_mfma_f32_16x16x32_bf16 v[82:85], v[170:173], v[204:207], v[82:85]
	v_mfma_f32_16x16x32_bf16 v[70:73], v[162:165], v[222:225], v[70:73]
	v_mfma_f32_16x16x32_bf16 v[66:69], v[170:173], v[222:225], v[66:69]
	v_mfma_f32_16x16x32_bf16 v[118:121], v[166:169], v[192:195], v[118:121]
	v_mfma_f32_16x16x32_bf16 v[114:117], v[174:177], v[192:195], v[114:117]
	v_mfma_f32_16x16x32_bf16 v[102:105], v[166:169], v[200:203], v[102:105]
	v_mfma_f32_16x16x32_bf16 v[98:101], v[174:177], v[200:203], v[98:101]
	v_mfma_f32_16x16x32_bf16 v[86:89], v[166:169], v[218:221], v[86:89]
	v_mfma_f32_16x16x32_bf16 v[82:85], v[174:177], v[218:221], v[82:85]
	v_mfma_f32_16x16x32_bf16 v[70:73], v[166:169], v[226:229], v[70:73]
	v_mfma_f32_16x16x32_bf16 v[66:69], v[174:177], v[226:229], v[66:69]
	s_setprio 0
	s_barrier
	s_add_i32 s3, s3, s2
	v_lshl_add_u64 v[152:153], v[152:153], 0, s[52:53]
	s_mov_b32 m0, s3
	ds_read_b128 v[188:191], v157 offset:49152
	ds_read_b128 v[192:195], v157 offset:50176
	ds_read_b128 v[196:199], v157 offset:51200
	ds_read_b128 v[200:203], v157 offset:52224
	ds_read_b128 v[204:207], v157 offset:53248
	ds_read_b128 v[218:221], v157 offset:54272
	ds_read_b128 v[222:225], v157 offset:55296
	ds_read_b128 v[226:229], v157 offset:56320
	global_load_lds_dwordx4 v[152:153], off
	s_add_i32 m0, s3, 0x2000
	s_add_u32 s18, s18, 0x80080
	v_lshl_add_u64 v[152:153], v[178:179], 0, s[52:53]
	s_addc_u32 s19, s19, 0
	s_add_i32 s3, s42, s2
	global_load_lds_dwordx4 v[152:153], off
	v_lshl_add_u64 v[152:153], s[18:19], 0, v[0:1]
	s_mov_b32 m0, s3
	s_nop 0
	global_load_lds_dwordx4 v[152:153], off
	v_lshl_add_u64 v[152:153], s[18:19], 0, v[130:131]
	s_add_i32 m0, s3, 0x2000
	s_nop 0
	global_load_lds_dwordx4 v[152:153], off
	v_lshl_add_u64 v[152:153], v[180:181], 0, s[52:53]
	s_mov_b32 m0, s26
	s_nop 0
	global_load_lds_dwordx4 v[152:153], off
	v_lshl_add_u64 v[152:153], v[182:183], 0, s[52:53]
	s_mov_b32 m0, s27
	s_nop 0
	global_load_lds_dwordx4 v[152:153], off
	s_waitcnt vmcnt(8)
	s_waitcnt lgkmcnt(0)
	s_waitcnt lgkmcnt(0)
	v_mfma_f32_16x16x32_bf16 v[62:65], v[140:143], v[188:191], v[62:65]
	v_mfma_f32_16x16x32_bf16 v[58:61], v[148:151], v[188:191], v[58:61]
	s_barrier
	s_setprio 1
	v_mfma_f32_16x16x32_bf16 v[46:49], v[140:143], v[196:199], v[46:49]
	v_mfma_f32_16x16x32_bf16 v[42:45], v[148:151], v[196:199], v[42:45]
	v_mfma_f32_16x16x32_bf16 v[30:33], v[140:143], v[204:207], v[30:33]
	v_mfma_f32_16x16x32_bf16 v[26:29], v[148:151], v[204:207], v[26:29]
	v_mfma_f32_16x16x32_bf16 v[14:17], v[140:143], v[222:225], v[14:17]
	v_mfma_f32_16x16x32_bf16 v[6:9], v[148:151], v[222:225], v[6:9]
	v_mfma_f32_16x16x32_bf16 v[62:65], v[144:147], v[192:195], v[62:65]
	v_mfma_f32_16x16x32_bf16 v[58:61], v[158:161], v[192:195], v[58:61]
	v_mfma_f32_16x16x32_bf16 v[46:49], v[144:147], v[200:203], v[46:49]
	v_mfma_f32_16x16x32_bf16 v[42:45], v[158:161], v[200:203], v[42:45]
	v_mfma_f32_16x16x32_bf16 v[30:33], v[144:147], v[218:221], v[30:33]
	v_mfma_f32_16x16x32_bf16 v[26:29], v[158:161], v[218:221], v[26:29]
	v_mfma_f32_16x16x32_bf16 v[14:17], v[144:147], v[226:229], v[14:17]
	v_mfma_f32_16x16x32_bf16 v[6:9], v[158:161], v[226:229], v[6:9]
	s_setprio 0
	s_setprio 1
	v_mfma_f32_16x16x32_bf16 v[54:57], v[162:165], v[188:191], v[54:57]
	v_mfma_f32_16x16x32_bf16 v[50:53], v[170:173], v[188:191], v[50:53]
	v_mfma_f32_16x16x32_bf16 v[38:41], v[162:165], v[196:199], v[38:41]
	v_mfma_f32_16x16x32_bf16 v[34:37], v[170:173], v[196:199], v[34:37]
	v_mfma_f32_16x16x32_bf16 v[22:25], v[162:165], v[204:207], v[22:25]
	v_mfma_f32_16x16x32_bf16 v[18:21], v[170:173], v[204:207], v[18:21]
	v_mfma_f32_16x16x32_bf16 v[10:13], v[162:165], v[222:225], v[10:13]
	v_mfma_f32_16x16x32_bf16 v[2:5], v[170:173], v[222:225], v[2:5]
	v_mfma_f32_16x16x32_bf16 v[54:57], v[166:169], v[192:195], v[54:57]
	v_mfma_f32_16x16x32_bf16 v[50:53], v[174:177], v[192:195], v[50:53]
	v_mfma_f32_16x16x32_bf16 v[38:41], v[166:169], v[200:203], v[38:41]
	v_mfma_f32_16x16x32_bf16 v[34:37], v[174:177], v[200:203], v[34:37]
	v_mfma_f32_16x16x32_bf16 v[22:25], v[166:169], v[218:221], v[22:25]
	v_mfma_f32_16x16x32_bf16 v[18:21], v[174:177], v[218:221], v[18:21]
	v_mfma_f32_16x16x32_bf16 v[10:13], v[166:169], v[226:229], v[10:13]
	v_mfma_f32_16x16x32_bf16 v[2:5], v[174:177], v[226:229], v[2:5]
	s_setprio 0
	s_barrier
	s_add_i32 s41, s41, 2
	s_add_u32 s16, s16, 0x100
	s_addc_u32 s17, s17, 0
	s_add_u32 s35, s35, 0x100
	s_addc_u32 s40, s40, 0
	s_cmp_gt_u32 s41, 29
	s_cbranch_scc0 .LBB0_377
	s_and_b64 vcc, exec, s[6:7]
	s_movk_i32 s40, 0x4000
	s_movk_i32 s41, 0x6000
	s_cbranch_vccz .LBB0_380
	s_barrier

.LBB0_399:
	s_add_u32 s3, s0, 0xfff80080
	s_addc_u32 s4, s1, -1
	s_add_i32 s42, 0, 0x10000
	s_cmp_eq_u32 s46, 28
	s_cselect_b32 s7, s8, s4
	s_cselect_b32 s6, s9, s3
	v_add_u32_e32 v0, s42, v206
	s_cselect_b32 s5, s19, s27
	s_cselect_b32 s4, s21, s26
	s_add_i32 s3, 0, 0x14000
	ds_read_b128 v[130:133], v0
	ds_read_b128 v[134:137], v0 offset:1024
	ds_read_b128 v[138:141], v0 offset:2048
	ds_read_b128 v[142:145], v0 offset:3072
	v_add_u32_e32 v0, s3, v206
	ds_read_b128 v[146:149], v0
	ds_read_b128 v[150:153], v0 offset:1024
	s_waitcnt lgkmcnt(0)
	ds_read_b128 v[154:157], v0 offset:2048
	ds_read_b128 v[158:161], v0 offset:3072
	v_lshl_add_u64 v[176:177], s[0:1], 0, v[170:171]
	s_add_i32 m0, s28, 0xc000
	ds_read_b128 v[196:199], v218
	ds_read_b128 v[200:203], v218 offset:1024
	ds_read_b128 v[220:223], v218 offset:2048
	ds_read_b128 v[224:227], v218 offset:3072
	ds_read_b128 v[228:231], v218 offset:4096
	ds_read_b128 v[232:235], v218 offset:5120
	ds_read_b128 v[236:239], v218 offset:6144
	ds_read_b128 v[240:243], v218 offset:7168
	global_load_lds_dwordx4 v[176:177], off
	v_lshl_add_u64 v[176:177], s[0:1], 0, v[172:173]
	s_add_i32 m0, s28, 0xe000
	s_nop 0
	global_load_lds_dwordx4 v[176:177], off
	s_waitcnt vmcnt(8)
	s_waitcnt lgkmcnt(0)
	s_waitcnt lgkmcnt(0)
	v_mfma_f32_16x16x32_bf16 v[126:129], v[130:133], v[196:199], v[126:129]
	v_mfma_f32_16x16x32_bf16 v[122:125], v[138:141], v[196:199], v[122:125]
	s_barrier
	s_setprio 1
	v_mfma_f32_16x16x32_bf16 v[118:121], v[130:133], v[220:223], v[118:121]
	v_mfma_f32_16x16x32_bf16 v[114:117], v[138:141], v[220:223], v[114:117]
	v_mfma_f32_16x16x32_bf16 v[110:113], v[130:133], v[228:231], v[110:113]
	v_mfma_f32_16x16x32_bf16 v[106:109], v[138:141], v[228:231], v[106:109]
	v_mfma_f32_16x16x32_bf16 v[102:105], v[130:133], v[236:239], v[102:105]
	v_mfma_f32_16x16x32_bf16 v[98:101], v[138:141], v[236:239], v[98:101]
	v_mfma_f32_16x16x32_bf16 v[126:129], v[134:137], v[200:203], v[126:129]
	v_mfma_f32_16x16x32_bf16 v[122:125], v[142:145], v[200:203], v[122:125]
	v_mfma_f32_16x16x32_bf16 v[118:121], v[134:137], v[224:227], v[118:121]
	v_mfma_f32_16x16x32_bf16 v[114:117], v[142:145], v[224:227], v[114:117]
	v_mfma_f32_16x16x32_bf16 v[110:113], v[134:137], v[232:235], v[110:113]
	v_mfma_f32_16x16x32_bf16 v[106:109], v[142:145], v[232:235], v[106:109]
	v_mfma_f32_16x16x32_bf16 v[102:105], v[134:137], v[240:243], v[102:105]
	v_mfma_f32_16x16x32_bf16 v[98:101], v[142:145], v[240:243], v[98:101]
	s_setprio 0
	s_setprio 1
	v_mfma_f32_16x16x32_bf16 v[94:97], v[146:149], v[196:199], v[94:97]
	v_mfma_f32_16x16x32_bf16 v[90:93], v[154:157], v[196:199], v[90:93]
	v_mfma_f32_16x16x32_bf16 v[86:89], v[146:149], v[220:223], v[86:89]
	v_mfma_f32_16x16x32_bf16 v[82:85], v[154:157], v[220:223], v[82:85]
	v_mfma_f32_16x16x32_bf16 v[78:81], v[146:149], v[228:231], v[78:81]
	v_mfma_f32_16x16x32_bf16 v[74:77], v[154:157], v[228:231], v[74:77]
	v_mfma_f32_16x16x32_bf16 v[70:73], v[146:149], v[236:239], v[70:73]
	v_mfma_f32_16x16x32_bf16 v[66:69], v[154:157], v[236:239], v[66:69]
	v_mfma_f32_16x16x32_bf16 v[94:97], v[150:153], v[200:203], v[94:97]
	v_mfma_f32_16x16x32_bf16 v[90:93], v[158:161], v[200:203], v[90:93]
	v_mfma_f32_16x16x32_bf16 v[86:89], v[150:153], v[224:227], v[86:89]
	v_mfma_f32_16x16x32_bf16 v[82:85], v[158:161], v[224:227], v[82:85]
	v_mfma_f32_16x16x32_bf16 v[78:81], v[150:153], v[232:235], v[78:81]
	v_mfma_f32_16x16x32_bf16 v[74:77], v[158:161], v[232:235], v[74:77]
	v_mfma_f32_16x16x32_bf16 v[70:73], v[150:153], v[240:243], v[70:73]
	v_mfma_f32_16x16x32_bf16 v[66:69], v[158:161], v[240:243], v[66:69]
	s_setprio 0
	s_barrier
	s_add_i32 s42, s42, s2
	v_lshl_add_u64 v[176:177], s[4:5], 0, v[166:167]
	s_mov_b32 m0, s42
	ds_read_b128 v[196:199], v218 offset:16384
	ds_read_b128 v[200:203], v218 offset:17408
	ds_read_b128 v[220:223], v218 offset:18432
	ds_read_b128 v[224:227], v218 offset:19456
	ds_read_b128 v[228:231], v218 offset:20480
	ds_read_b128 v[232:235], v218 offset:21504
	ds_read_b128 v[236:239], v218 offset:22528
	ds_read_b128 v[240:243], v218 offset:23552
	global_load_lds_dwordx4 v[176:177], off
	s_add_i32 m0, s42, 0x2000
	s_add_u32 s56, s4, 0x80000
	v_lshl_add_u64 v[178:179], s[4:5], 0, v[162:163]
	s_addc_u32 s57, s5, 0
	s_add_i32 s3, s3, s2
	global_load_lds_dwordx4 v[178:179], off
	v_lshl_add_u64 v[244:245], s[56:57], 0, v[166:167]
	s_mov_b32 m0, s3
	v_lshl_add_u64 v[246:247], s[6:7], 0, v[164:165]
	global_load_lds_dwordx4 v[244:245], off
	v_lshl_add_u64 v[244:245], s[56:57], 0, v[162:163]
	s_add_i32 m0, s3, 0x2000
	s_nop 0
	global_load_lds_dwordx4 v[244:245], off
	v_lshl_add_u64 v[244:245], s[6:7], 0, v[168:169]
	s_mov_b32 m0, s28
	s_nop 0
	global_load_lds_dwordx4 v[244:245], off
	s_mov_b32 m0, s29
	s_nop 0
	global_load_lds_dwordx4 v[246:247], off
	s_waitcnt vmcnt(8)
	s_waitcnt lgkmcnt(0)
	s_waitcnt lgkmcnt(0)
	v_mfma_f32_16x16x32_bf16 v[62:65], v[130:133], v[196:199], v[62:65]
	v_mfma_f32_16x16x32_bf16 v[58:61], v[138:141], v[196:199], v[58:61]
	s_barrier
	s_setprio 1
	v_mfma_f32_16x16x32_bf16 v[54:57], v[130:133], v[220:223], v[54:57]
	v_mfma_f32_16x16x32_bf16 v[50:53], v[138:141], v[220:223], v[50:53]
	v_mfma_f32_16x16x32_bf16 v[46:49], v[130:133], v[228:231], v[46:49]
	v_mfma_f32_16x16x32_bf16 v[42:45], v[138:141], v[228:231], v[42:45]
	v_mfma_f32_16x16x32_bf16 v[38:41], v[130:133], v[236:239], v[38:41]
	v_mfma_f32_16x16x32_bf16 v[34:37], v[138:141], v[236:239], v[34:37]
	v_mfma_f32_16x16x32_bf16 v[62:65], v[134:137], v[200:203], v[62:65]
	v_mfma_f32_16x16x32_bf16 v[58:61], v[142:145], v[200:203], v[58:61]
	v_mfma_f32_16x16x32_bf16 v[54:57], v[134:137], v[224:227], v[54:57]
	v_mfma_f32_16x16x32_bf16 v[50:53], v[142:145], v[224:227], v[50:53]
	v_mfma_f32_16x16x32_bf16 v[46:49], v[134:137], v[232:235], v[46:49]
	v_mfma_f32_16x16x32_bf16 v[42:45], v[142:145], v[232:235], v[42:45]
	v_mfma_f32_16x16x32_bf16 v[38:41], v[134:137], v[240:243], v[38:41]
	v_mfma_f32_16x16x32_bf16 v[34:37], v[142:145], v[240:243], v[34:37]
	s_setprio 0
	s_setprio 1
	v_mfma_f32_16x16x32_bf16 v[30:33], v[146:149], v[196:199], v[30:33]
	v_mfma_f32_16x16x32_bf16 v[26:29], v[154:157], v[196:199], v[26:29]
	v_mfma_f32_16x16x32_bf16 v[22:25], v[146:149], v[220:223], v[22:25]
	v_mfma_f32_16x16x32_bf16 v[18:21], v[154:157], v[220:223], v[18:21]
	v_mfma_f32_16x16x32_bf16 v[14:17], v[146:149], v[228:231], v[14:17]
	v_mfma_f32_16x16x32_bf16 v[10:13], v[154:157], v[228:231], v[10:13]
	v_mfma_f32_16x16x32_bf16 v[6:9], v[146:149], v[236:239], v[6:9]
	v_mfma_f32_16x16x32_bf16 v[2:5], v[154:157], v[236:239], v[2:5]
	v_mfma_f32_16x16x32_bf16 v[30:33], v[150:153], v[200:203], v[30:33]
	v_mfma_f32_16x16x32_bf16 v[26:29], v[158:161], v[200:203], v[26:29]
	v_mfma_f32_16x16x32_bf16 v[22:25], v[150:153], v[224:227], v[22:25]
	v_mfma_f32_16x16x32_bf16 v[18:21], v[158:161], v[224:227], v[18:21]
	v_mfma_f32_16x16x32_bf16 v[14:17], v[150:153], v[232:235], v[14:17]
	v_mfma_f32_16x16x32_bf16 v[10:13], v[158:161], v[232:235], v[10:13]
	v_mfma_f32_16x16x32_bf16 v[6:9], v[150:153], v[240:243], v[6:9]
	v_mfma_f32_16x16x32_bf16 v[2:5], v[158:161], v[240:243], v[2:5]
	s_setprio 0
	s_barrier
	s_add_i32 s3, 0, 0x18000
	v_add_u32_e32 v0, s3, v206
	s_add_i32 s42, 0, 0x1c000
	ds_read_b128 v[130:133], v0
	ds_read_b128 v[134:137], v0 offset:1024
	ds_read_b128 v[138:141], v0 offset:2048
	ds_read_b128 v[142:145], v0 offset:3072
	v_add_u32_e32 v0, s42, v206
	ds_read_b128 v[146:149], v0
	ds_read_b128 v[150:153], v0 offset:1024
	ds_read_b128 v[154:157], v0 offset:2048
	ds_read_b128 v[158:161], v0 offset:3072
	s_add_u32 s6, s6, 0x80000
	s_addc_u32 s7, s7, 0
	s_mov_b32 m0, s30
	v_lshl_add_u64 v[248:249], s[6:7], 0, v[168:169]
	ds_read_b128 v[196:199], v218 offset:32768
	ds_read_b128 v[200:203], v218 offset:33792
	ds_read_b128 v[220:223], v218 offset:34816
	ds_read_b128 v[224:227], v218 offset:35840
	ds_read_b128 v[228:231], v218 offset:36864
	ds_read_b128 v[232:235], v218 offset:37888
	ds_read_b128 v[236:239], v218 offset:38912
	ds_read_b128 v[240:243], v218 offset:39936
	global_load_lds_dwordx4 v[248:249], off
	v_lshl_add_u64 v[248:249], s[6:7], 0, v[164:165]
	s_mov_b32 m0, s31
	s_nop 0
	global_load_lds_dwordx4 v[248:249], off
	s_waitcnt vmcnt(8)
	s_waitcnt lgkmcnt(0)
	s_waitcnt lgkmcnt(0)
	v_mfma_f32_16x16x32_bf16 v[126:129], v[130:133], v[196:199], v[126:129]
	v_mfma_f32_16x16x32_bf16 v[122:125], v[138:141], v[196:199], v[122:125]
	s_barrier
	s_setprio 1
	v_mfma_f32_16x16x32_bf16 v[118:121], v[130:133], v[220:223], v[118:121]
	v_mfma_f32_16x16x32_bf16 v[114:117], v[138:141], v[220:223], v[114:117]
	v_mfma_f32_16x16x32_bf16 v[110:113], v[130:133], v[228:231], v[110:113]
	v_mfma_f32_16x16x32_bf16 v[106:109], v[138:141], v[228:231], v[106:109]
	v_mfma_f32_16x16x32_bf16 v[102:105], v[130:133], v[236:239], v[102:105]
	v_mfma_f32_16x16x32_bf16 v[98:101], v[138:141], v[236:239], v[98:101]
	v_mfma_f32_16x16x32_bf16 v[126:129], v[134:137], v[200:203], v[126:129]
	v_mfma_f32_16x16x32_bf16 v[122:125], v[142:145], v[200:203], v[122:125]
	v_mfma_f32_16x16x32_bf16 v[118:121], v[134:137], v[224:227], v[118:121]
	v_mfma_f32_16x16x32_bf16 v[114:117], v[142:145], v[224:227], v[114:117]
	v_mfma_f32_16x16x32_bf16 v[110:113], v[134:137], v[232:235], v[110:113]
	v_mfma_f32_16x16x32_bf16 v[106:109], v[142:145], v[232:235], v[106:109]
	v_mfma_f32_16x16x32_bf16 v[102:105], v[134:137], v[240:243], v[102:105]
	v_mfma_f32_16x16x32_bf16 v[98:101], v[142:145], v[240:243], v[98:101]
	s_setprio 0
	s_setprio 1
	v_mfma_f32_16x16x32_bf16 v[94:97], v[146:149], v[196:199], v[94:97]
	v_mfma_f32_16x16x32_bf16 v[90:93], v[154:157], v[196:199], v[90:93]
	v_mfma_f32_16x16x32_bf16 v[86:89], v[146:149], v[220:223], v[86:89]
	v_mfma_f32_16x16x32_bf16 v[82:85], v[154:157], v[220:223], v[82:85]
	v_mfma_f32_16x16x32_bf16 v[78:81], v[146:149], v[228:231], v[78:81]
	v_mfma_f32_16x16x32_bf16 v[74:77], v[154:157], v[228:231], v[74:77]
	v_mfma_f32_16x16x32_bf16 v[70:73], v[146:149], v[236:239], v[70:73]
	v_mfma_f32_16x16x32_bf16 v[66:69], v[154:157], v[236:239], v[66:69]
	v_mfma_f32_16x16x32_bf16 v[94:97], v[150:153], v[200:203], v[94:97]
	v_mfma_f32_16x16x32_bf16 v[90:93], v[158:161], v[200:203], v[90:93]
	v_mfma_f32_16x16x32_bf16 v[86:89], v[150:153], v[224:227], v[86:89]
	v_mfma_f32_16x16x32_bf16 v[82:85], v[158:161], v[224:227], v[82:85]
	v_mfma_f32_16x16x32_bf16 v[78:81], v[150:153], v[232:235], v[78:81]
	v_mfma_f32_16x16x32_bf16 v[74:77], v[158:161], v[232:235], v[74:77]
	v_mfma_f32_16x16x32_bf16 v[70:73], v[150:153], v[240:243], v[70:73]
	v_mfma_f32_16x16x32_bf16 v[66:69], v[158:161], v[240:243], v[66:69]
	s_setprio 0
	s_barrier
	s_add_i32 s3, s3, s2
	v_lshl_add_u64 v[176:177], v[176:177], 0, s[52:53]
	s_mov_b32 m0, s3
	ds_read_b128 v[196:199], v218 offset:49152
	ds_read_b128 v[200:203], v218 offset:50176
	ds_read_b128 v[220:223], v218 offset:51200
	ds_read_b128 v[224:227], v218 offset:52224
	ds_read_b128 v[228:231], v218 offset:53248
	ds_read_b128 v[232:235], v218 offset:54272
	ds_read_b128 v[236:239], v218 offset:55296
	ds_read_b128 v[240:243], v218 offset:56320
	global_load_lds_dwordx4 v[176:177], off
	s_add_i32 m0, s3, 0x2000
	s_add_u32 s4, s4, 0x80080
	v_lshl_add_u64 v[176:177], v[178:179], 0, s[52:53]
	s_addc_u32 s5, s5, 0
	s_add_i32 s3, s42, s2
	global_load_lds_dwordx4 v[176:177], off
	v_lshl_add_u64 v[176:177], s[4:5], 0, v[166:167]
	s_mov_b32 m0, s3
	s_nop 0
	global_load_lds_dwordx4 v[176:177], off
	v_lshl_add_u64 v[176:177], s[4:5], 0, v[162:163]
	s_add_i32 m0, s3, 0x2000
	s_nop 0
	global_load_lds_dwordx4 v[176:177], off
	v_lshl_add_u64 v[176:177], v[244:245], 0, s[52:53]
	s_mov_b32 m0, s35
	s_nop 0
	global_load_lds_dwordx4 v[176:177], off
	v_lshl_add_u64 v[176:177], v[246:247], 0, s[52:53]
	s_mov_b32 m0, s40
	s_nop 0
	global_load_lds_dwordx4 v[176:177], off
	s_waitcnt vmcnt(8)
	s_waitcnt lgkmcnt(0)
	s_waitcnt lgkmcnt(0)
	v_mfma_f32_16x16x32_bf16 v[62:65], v[130:133], v[196:199], v[62:65]
	v_mfma_f32_16x16x32_bf16 v[58:61], v[138:141], v[196:199], v[58:61]
	s_barrier
	s_setprio 1
	v_mfma_f32_16x16x32_bf16 v[54:57], v[130:133], v[220:223], v[54:57]
	v_mfma_f32_16x16x32_bf16 v[50:53], v[138:141], v[220:223], v[50:53]
	v_mfma_f32_16x16x32_bf16 v[46:49], v[130:133], v[228:231], v[46:49]
	v_mfma_f32_16x16x32_bf16 v[42:45], v[138:141], v[228:231], v[42:45]
	v_mfma_f32_16x16x32_bf16 v[38:41], v[130:133], v[236:239], v[38:41]
	v_mfma_f32_16x16x32_bf16 v[34:37], v[138:141], v[236:239], v[34:37]
	v_mfma_f32_16x16x32_bf16 v[62:65], v[134:137], v[200:203], v[62:65]
	v_mfma_f32_16x16x32_bf16 v[58:61], v[142:145], v[200:203], v[58:61]
	v_mfma_f32_16x16x32_bf16 v[54:57], v[134:137], v[224:227], v[54:57]
	v_mfma_f32_16x16x32_bf16 v[50:53], v[142:145], v[224:227], v[50:53]
	v_mfma_f32_16x16x32_bf16 v[46:49], v[134:137], v[232:235], v[46:49]
	v_mfma_f32_16x16x32_bf16 v[42:45], v[142:145], v[232:235], v[42:45]
	v_mfma_f32_16x16x32_bf16 v[38:41], v[134:137], v[240:243], v[38:41]
	v_mfma_f32_16x16x32_bf16 v[34:37], v[142:145], v[240:243], v[34:37]
	s_setprio 0
	s_setprio 1
	v_mfma_f32_16x16x32_bf16 v[30:33], v[146:149], v[196:199], v[30:33]
	v_mfma_f32_16x16x32_bf16 v[26:29], v[154:157], v[196:199], v[26:29]
	v_mfma_f32_16x16x32_bf16 v[22:25], v[146:149], v[220:223], v[22:25]
	v_mfma_f32_16x16x32_bf16 v[18:21], v[154:157], v[220:223], v[18:21]
	v_mfma_f32_16x16x32_bf16 v[14:17], v[146:149], v[228:231], v[14:17]
	v_mfma_f32_16x16x32_bf16 v[10:13], v[154:157], v[228:231], v[10:13]
	v_mfma_f32_16x16x32_bf16 v[6:9], v[146:149], v[236:239], v[6:9]
	v_mfma_f32_16x16x32_bf16 v[2:5], v[154:157], v[236:239], v[2:5]
	v_mfma_f32_16x16x32_bf16 v[30:33], v[150:153], v[200:203], v[30:33]
	v_mfma_f32_16x16x32_bf16 v[26:29], v[158:161], v[200:203], v[26:29]
	v_mfma_f32_16x16x32_bf16 v[22:25], v[150:153], v[224:227], v[22:25]
	v_mfma_f32_16x16x32_bf16 v[18:21], v[158:161], v[224:227], v[18:21]
	v_mfma_f32_16x16x32_bf16 v[14:17], v[150:153], v[232:235], v[14:17]
	v_mfma_f32_16x16x32_bf16 v[10:13], v[158:161], v[232:235], v[10:13]
	v_mfma_f32_16x16x32_bf16 v[6:9], v[150:153], v[240:243], v[6:9]
	v_mfma_f32_16x16x32_bf16 v[2:5], v[158:161], v[240:243], v[2:5]
	s_setprio 0
	s_barrier
	s_add_i32 s46, s46, 2
	s_add_u32 s0, s0, 0x100
	s_addc_u32 s1, s1, 0
	s_add_u32 s26, s26, 0x100
	s_addc_u32 s27, s27, 0
	s_cmp_gt_u32 s46, 29
	s_cbranch_scc0 .LBB0_399
	s_and_b64 vcc, exec, s[14:15]
	s_cbranch_vccz .LBB0_402
	s_barrier

.LBB0_846:
	s_add_u32 s3, s0, 0xfff80080
	s_addc_u32 s18, s1, -1
	s_add_i32 s42, 0, 0x10000
	s_cmp_eq_u32 s41, 28
	s_cselect_b32 s21, s13, s18
	s_cselect_b32 s20, s31, s3
	s_cselect_b32 s19, s11, s40
	s_cselect_b32 s18, s34, s35
	s_add_i32 s3, 0, 0x14000
	v_add_u32_e32 v152, s42, v163
	v_add_u32_e32 v160, s3, v163
	ds_read_b128 v[140:143], v152
	ds_read_b128 v[144:147], v152 offset:1024
	ds_read_b128 v[148:151], v152 offset:2048
	ds_read_b128 v[152:155], v152 offset:3072
	ds_read_b128 v[156:159], v160
	ds_read_b128 v[166:169], v160 offset:1024
	ds_read_b128 v[170:173], v160 offset:2048
	ds_read_b128 v[174:177], v160 offset:3072
	v_lshl_add_u64 v[160:161], s[0:1], 0, v[136:137]
	s_add_i32 m0, s22, 0xc000
	ds_read_b128 v[188:191], v165
	ds_read_b128 v[192:195], v165 offset:1024
	ds_read_b128 v[196:199], v165 offset:2048
	ds_read_b128 v[200:203], v165 offset:3072
	ds_read_b128 v[204:207], v165 offset:4096
	ds_read_b128 v[218:221], v165 offset:5120
	ds_read_b128 v[222:225], v165 offset:6144
	ds_read_b128 v[226:229], v165 offset:7168
	global_load_lds_dwordx4 v[160:161], off
	v_lshl_add_u64 v[160:161], s[0:1], 0, v[138:139]
	s_add_i32 m0, s22, 0xe000
	s_nop 0
	global_load_lds_dwordx4 v[160:161], off
	s_waitcnt vmcnt(8)
	s_waitcnt lgkmcnt(0)
	s_waitcnt lgkmcnt(0)
	v_mfma_f32_16x16x32_bf16 v[126:129], v[140:143], v[188:191], v[126:129]
	v_mfma_f32_16x16x32_bf16 v[122:125], v[148:151], v[188:191], v[122:125]
	s_barrier
	s_setprio 1
	v_mfma_f32_16x16x32_bf16 v[110:113], v[140:143], v[196:199], v[110:113]
	v_mfma_f32_16x16x32_bf16 v[106:109], v[148:151], v[196:199], v[106:109]
	v_mfma_f32_16x16x32_bf16 v[94:97], v[140:143], v[204:207], v[94:97]
	v_mfma_f32_16x16x32_bf16 v[90:93], v[148:151], v[204:207], v[90:93]
	v_mfma_f32_16x16x32_bf16 v[78:81], v[140:143], v[222:225], v[78:81]
	v_mfma_f32_16x16x32_bf16 v[74:77], v[148:151], v[222:225], v[74:77]
	v_mfma_f32_16x16x32_bf16 v[126:129], v[144:147], v[192:195], v[126:129]
	v_mfma_f32_16x16x32_bf16 v[122:125], v[152:155], v[192:195], v[122:125]
	v_mfma_f32_16x16x32_bf16 v[110:113], v[144:147], v[200:203], v[110:113]
	v_mfma_f32_16x16x32_bf16 v[106:109], v[152:155], v[200:203], v[106:109]
	v_mfma_f32_16x16x32_bf16 v[94:97], v[144:147], v[218:221], v[94:97]
	v_mfma_f32_16x16x32_bf16 v[90:93], v[152:155], v[218:221], v[90:93]
	v_mfma_f32_16x16x32_bf16 v[78:81], v[144:147], v[226:229], v[78:81]
	v_mfma_f32_16x16x32_bf16 v[74:77], v[152:155], v[226:229], v[74:77]
	s_setprio 0
	s_setprio 1
	v_mfma_f32_16x16x32_bf16 v[118:121], v[156:159], v[188:191], v[118:121]
	v_mfma_f32_16x16x32_bf16 v[114:117], v[170:173], v[188:191], v[114:117]
	v_mfma_f32_16x16x32_bf16 v[102:105], v[156:159], v[196:199], v[102:105]
	v_mfma_f32_16x16x32_bf16 v[98:101], v[170:173], v[196:199], v[98:101]
	v_mfma_f32_16x16x32_bf16 v[86:89], v[156:159], v[204:207], v[86:89]
	v_mfma_f32_16x16x32_bf16 v[82:85], v[170:173], v[204:207], v[82:85]
	v_mfma_f32_16x16x32_bf16 v[70:73], v[156:159], v[222:225], v[70:73]
	v_mfma_f32_16x16x32_bf16 v[66:69], v[170:173], v[222:225], v[66:69]
	v_mfma_f32_16x16x32_bf16 v[118:121], v[166:169], v[192:195], v[118:121]
	v_mfma_f32_16x16x32_bf16 v[114:117], v[174:177], v[192:195], v[114:117]
	v_mfma_f32_16x16x32_bf16 v[102:105], v[166:169], v[200:203], v[102:105]
	v_mfma_f32_16x16x32_bf16 v[98:101], v[174:177], v[200:203], v[98:101]
	v_mfma_f32_16x16x32_bf16 v[86:89], v[166:169], v[218:221], v[86:89]
	v_mfma_f32_16x16x32_bf16 v[82:85], v[174:177], v[218:221], v[82:85]
	v_mfma_f32_16x16x32_bf16 v[70:73], v[166:169], v[226:229], v[70:73]
	v_mfma_f32_16x16x32_bf16 v[66:69], v[174:177], v[226:229], v[66:69]
	s_setprio 0
	s_barrier
	s_add_i32 s42, s42, s2
	v_lshl_add_u64 v[160:161], s[18:19], 0, v[0:1]
	s_mov_b32 m0, s42
	ds_read_b128 v[188:191], v165 offset:16384
	ds_read_b128 v[192:195], v165 offset:17408
	ds_read_b128 v[196:199], v165 offset:18432
	ds_read_b128 v[200:203], v165 offset:19456
	ds_read_b128 v[204:207], v165 offset:20480
	ds_read_b128 v[218:221], v165 offset:21504
	ds_read_b128 v[222:225], v165 offset:22528
	ds_read_b128 v[226:229], v165 offset:23552
	global_load_lds_dwordx4 v[160:161], off
	s_add_i32 m0, s42, 0x2000
	s_add_u32 s44, s18, 0x80000
	v_lshl_add_u64 v[178:179], s[18:19], 0, v[130:131]
	s_addc_u32 s45, s19, 0
	s_add_i32 s3, s3, s2
	global_load_lds_dwordx4 v[178:179], off
	v_lshl_add_u64 v[180:181], s[44:45], 0, v[0:1]
	s_mov_b32 m0, s3
	v_lshl_add_u64 v[182:183], s[20:21], 0, v[132:133]
	global_load_lds_dwordx4 v[180:181], off
	v_lshl_add_u64 v[180:181], s[44:45], 0, v[130:131]
	s_add_i32 m0, s3, 0x2000
	s_nop 0
	global_load_lds_dwordx4 v[180:181], off
	v_lshl_add_u64 v[180:181], s[20:21], 0, v[134:135]
	s_mov_b32 m0, s22
	s_nop 0
	global_load_lds_dwordx4 v[180:181], off
	s_mov_b32 m0, s23
	s_nop 0
	global_load_lds_dwordx4 v[182:183], off
	s_waitcnt vmcnt(8)
	s_waitcnt lgkmcnt(0)
	s_waitcnt lgkmcnt(0)
	v_mfma_f32_16x16x32_bf16 v[62:65], v[140:143], v[188:191], v[62:65]
	v_mfma_f32_16x16x32_bf16 v[58:61], v[148:151], v[188:191], v[58:61]
	s_barrier
	s_setprio 1
	v_mfma_f32_16x16x32_bf16 v[46:49], v[140:143], v[196:199], v[46:49]
	v_mfma_f32_16x16x32_bf16 v[42:45], v[148:151], v[196:199], v[42:45]
	v_mfma_f32_16x16x32_bf16 v[30:33], v[140:143], v[204:207], v[30:33]
	v_mfma_f32_16x16x32_bf16 v[26:29], v[148:151], v[204:207], v[26:29]
	v_mfma_f32_16x16x32_bf16 v[14:17], v[140:143], v[222:225], v[14:17]
	v_mfma_f32_16x16x32_bf16 v[10:13], v[148:151], v[222:225], v[10:13]
	v_mfma_f32_16x16x32_bf16 v[62:65], v[144:147], v[192:195], v[62:65]
	v_mfma_f32_16x16x32_bf16 v[58:61], v[152:155], v[192:195], v[58:61]
	v_mfma_f32_16x16x32_bf16 v[46:49], v[144:147], v[200:203], v[46:49]
	v_mfma_f32_16x16x32_bf16 v[42:45], v[152:155], v[200:203], v[42:45]
	v_mfma_f32_16x16x32_bf16 v[30:33], v[144:147], v[218:221], v[30:33]
	v_mfma_f32_16x16x32_bf16 v[26:29], v[152:155], v[218:221], v[26:29]
	v_mfma_f32_16x16x32_bf16 v[14:17], v[144:147], v[226:229], v[14:17]
	v_mfma_f32_16x16x32_bf16 v[10:13], v[152:155], v[226:229], v[10:13]
	s_setprio 0
	s_setprio 1
	v_mfma_f32_16x16x32_bf16 v[54:57], v[156:159], v[188:191], v[54:57]
	v_mfma_f32_16x16x32_bf16 v[50:53], v[170:173], v[188:191], v[50:53]
	v_mfma_f32_16x16x32_bf16 v[38:41], v[156:159], v[196:199], v[38:41]
	v_mfma_f32_16x16x32_bf16 v[34:37], v[170:173], v[196:199], v[34:37]
	v_mfma_f32_16x16x32_bf16 v[22:25], v[156:159], v[204:207], v[22:25]
	v_mfma_f32_16x16x32_bf16 v[18:21], v[170:173], v[204:207], v[18:21]
	v_mfma_f32_16x16x32_bf16 v[6:9], v[156:159], v[222:225], v[6:9]
	v_mfma_f32_16x16x32_bf16 v[2:5], v[170:173], v[222:225], v[2:5]
	v_mfma_f32_16x16x32_bf16 v[54:57], v[166:169], v[192:195], v[54:57]
	v_mfma_f32_16x16x32_bf16 v[50:53], v[174:177], v[192:195], v[50:53]
	v_mfma_f32_16x16x32_bf16 v[38:41], v[166:169], v[200:203], v[38:41]
	v_mfma_f32_16x16x32_bf16 v[34:37], v[174:177], v[200:203], v[34:37]
	v_mfma_f32_16x16x32_bf16 v[22:25], v[166:169], v[218:221], v[22:25]
	v_mfma_f32_16x16x32_bf16 v[18:21], v[174:177], v[218:221], v[18:21]
	v_mfma_f32_16x16x32_bf16 v[6:9], v[166:169], v[226:229], v[6:9]
	v_mfma_f32_16x16x32_bf16 v[2:5], v[174:177], v[226:229], v[2:5]
	s_setprio 0
	s_barrier
	s_add_i32 s3, 0, 0x18000
	s_add_i32 s42, 0, 0x1c000
	v_add_u32_e32 v152, s3, v163
	v_add_u32_e32 v174, s42, v163
	ds_read_b128 v[140:143], v152
	ds_read_b128 v[144:147], v152 offset:1024
	ds_read_b128 v[148:151], v152 offset:2048
	ds_read_b128 v[152:155], v152 offset:3072
	ds_read_b128 v[156:159], v174
	ds_read_b128 v[166:169], v174 offset:1024
	ds_read_b128 v[170:173], v174 offset:2048
	ds_read_b128 v[174:177], v174 offset:3072
	s_add_u32 s20, s20, 0x80000
	s_addc_u32 s21, s21, 0
	s_mov_b32 m0, s24
	v_lshl_add_u64 v[184:185], s[20:21], 0, v[134:135]
	ds_read_b128 v[188:191], v165 offset:32768
	ds_read_b128 v[192:195], v165 offset:33792
	ds_read_b128 v[196:199], v165 offset:34816
	ds_read_b128 v[200:203], v165 offset:35840
	ds_read_b128 v[204:207], v165 offset:36864
	ds_read_b128 v[218:221], v165 offset:37888
	ds_read_b128 v[222:225], v165 offset:38912
	ds_read_b128 v[226:229], v165 offset:39936
	global_load_lds_dwordx4 v[184:185], off
	v_lshl_add_u64 v[184:185], s[20:21], 0, v[132:133]
	s_mov_b32 m0, s25
	s_nop 0
	global_load_lds_dwordx4 v[184:185], off
	s_waitcnt vmcnt(8)
	s_waitcnt lgkmcnt(0)
	s_waitcnt lgkmcnt(0)
	v_mfma_f32_16x16x32_bf16 v[126:129], v[140:143], v[188:191], v[126:129]
	v_mfma_f32_16x16x32_bf16 v[122:125], v[148:151], v[188:191], v[122:125]
	s_barrier
	s_setprio 1
	v_mfma_f32_16x16x32_bf16 v[110:113], v[140:143], v[196:199], v[110:113]
	v_mfma_f32_16x16x32_bf16 v[106:109], v[148:151], v[196:199], v[106:109]
	v_mfma_f32_16x16x32_bf16 v[94:97], v[140:143], v[204:207], v[94:97]
	v_mfma_f32_16x16x32_bf16 v[90:93], v[148:151], v[204:207], v[90:93]
	v_mfma_f32_16x16x32_bf16 v[78:81], v[140:143], v[222:225], v[78:81]
	v_mfma_f32_16x16x32_bf16 v[74:77], v[148:151], v[222:225], v[74:77]
	v_mfma_f32_16x16x32_bf16 v[126:129], v[144:147], v[192:195], v[126:129]
	v_mfma_f32_16x16x32_bf16 v[122:125], v[152:155], v[192:195], v[122:125]
	v_mfma_f32_16x16x32_bf16 v[110:113], v[144:147], v[200:203], v[110:113]
	v_mfma_f32_16x16x32_bf16 v[106:109], v[152:155], v[200:203], v[106:109]
	v_mfma_f32_16x16x32_bf16 v[94:97], v[144:147], v[218:221], v[94:97]
	v_mfma_f32_16x16x32_bf16 v[90:93], v[152:155], v[218:221], v[90:93]
	v_mfma_f32_16x16x32_bf16 v[78:81], v[144:147], v[226:229], v[78:81]
	v_mfma_f32_16x16x32_bf16 v[74:77], v[152:155], v[226:229], v[74:77]
	s_setprio 0
	s_setprio 1
	v_mfma_f32_16x16x32_bf16 v[118:121], v[156:159], v[188:191], v[118:121]
	v_mfma_f32_16x16x32_bf16 v[114:117], v[170:173], v[188:191], v[114:117]
	v_mfma_f32_16x16x32_bf16 v[102:105], v[156:159], v[196:199], v[102:105]
	v_mfma_f32_16x16x32_bf16 v[98:101], v[170:173], v[196:199], v[98:101]
	v_mfma_f32_16x16x32_bf16 v[86:89], v[156:159], v[204:207], v[86:89]
	v_mfma_f32_16x16x32_bf16 v[82:85], v[170:173], v[204:207], v[82:85]
	v_mfma_f32_16x16x32_bf16 v[70:73], v[156:159], v[222:225], v[70:73]
	v_mfma_f32_16x16x32_bf16 v[66:69], v[170:173], v[222:225], v[66:69]
	v_mfma_f32_16x16x32_bf16 v[118:121], v[166:169], v[192:195], v[118:121]
	v_mfma_f32_16x16x32_bf16 v[114:117], v[174:177], v[192:195], v[114:117]
	v_mfma_f32_16x16x32_bf16 v[102:105], v[166:169], v[200:203], v[102:105]
	v_mfma_f32_16x16x32_bf16 v[98:101], v[174:177], v[200:203], v[98:101]
	v_mfma_f32_16x16x32_bf16 v[86:89], v[166:169], v[218:221], v[86:89]
	v_mfma_f32_16x16x32_bf16 v[82:85], v[174:177], v[218:221], v[82:85]
	v_mfma_f32_16x16x32_bf16 v[70:73], v[166:169], v[226:229], v[70:73]
	v_mfma_f32_16x16x32_bf16 v[66:69], v[174:177], v[226:229], v[66:69]
	s_setprio 0
	s_barrier
	s_add_i32 s3, s3, s2
	v_lshl_add_u64 v[160:161], v[160:161], 0, s[52:53]
	s_mov_b32 m0, s3
	ds_read_b128 v[188:191], v165 offset:49152
	ds_read_b128 v[192:195], v165 offset:50176
	ds_read_b128 v[196:199], v165 offset:51200
	ds_read_b128 v[200:203], v165 offset:52224
	ds_read_b128 v[204:207], v165 offset:53248
	ds_read_b128 v[218:221], v165 offset:54272
	ds_read_b128 v[222:225], v165 offset:55296
	ds_read_b128 v[226:229], v165 offset:56320
	global_load_lds_dwordx4 v[160:161], off
	s_add_i32 m0, s3, 0x2000
	s_add_u32 s18, s18, 0x80080
	v_lshl_add_u64 v[160:161], v[178:179], 0, s[52:53]
	s_addc_u32 s19, s19, 0
	s_add_i32 s3, s42, s2
	global_load_lds_dwordx4 v[160:161], off
	v_lshl_add_u64 v[160:161], s[18:19], 0, v[0:1]
	s_mov_b32 m0, s3
	s_nop 0
	global_load_lds_dwordx4 v[160:161], off
	v_lshl_add_u64 v[160:161], s[18:19], 0, v[130:131]
	s_add_i32 m0, s3, 0x2000
	s_nop 0
	global_load_lds_dwordx4 v[160:161], off
	v_lshl_add_u64 v[160:161], v[180:181], 0, s[52:53]
	s_mov_b32 m0, s26
	s_nop 0
	global_load_lds_dwordx4 v[160:161], off
	v_lshl_add_u64 v[160:161], v[182:183], 0, s[52:53]
	s_mov_b32 m0, s27
	s_nop 0
	global_load_lds_dwordx4 v[160:161], off
	s_waitcnt vmcnt(8)
	s_waitcnt lgkmcnt(0)
	s_waitcnt lgkmcnt(0)
	v_mfma_f32_16x16x32_bf16 v[62:65], v[140:143], v[188:191], v[62:65]
	v_mfma_f32_16x16x32_bf16 v[58:61], v[148:151], v[188:191], v[58:61]
	s_barrier
	s_setprio 1
	v_mfma_f32_16x16x32_bf16 v[46:49], v[140:143], v[196:199], v[46:49]
	v_mfma_f32_16x16x32_bf16 v[42:45], v[148:151], v[196:199], v[42:45]
	v_mfma_f32_16x16x32_bf16 v[30:33], v[140:143], v[204:207], v[30:33]
	v_mfma_f32_16x16x32_bf16 v[26:29], v[148:151], v[204:207], v[26:29]
	v_mfma_f32_16x16x32_bf16 v[14:17], v[140:143], v[222:225], v[14:17]
	v_mfma_f32_16x16x32_bf16 v[10:13], v[148:151], v[222:225], v[10:13]
	v_mfma_f32_16x16x32_bf16 v[62:65], v[144:147], v[192:195], v[62:65]
	v_mfma_f32_16x16x32_bf16 v[58:61], v[152:155], v[192:195], v[58:61]
	v_mfma_f32_16x16x32_bf16 v[46:49], v[144:147], v[200:203], v[46:49]
	v_mfma_f32_16x16x32_bf16 v[42:45], v[152:155], v[200:203], v[42:45]
	v_mfma_f32_16x16x32_bf16 v[30:33], v[144:147], v[218:221], v[30:33]
	v_mfma_f32_16x16x32_bf16 v[26:29], v[152:155], v[218:221], v[26:29]
	v_mfma_f32_16x16x32_bf16 v[14:17], v[144:147], v[226:229], v[14:17]
	v_mfma_f32_16x16x32_bf16 v[10:13], v[152:155], v[226:229], v[10:13]
	s_setprio 0
	s_setprio 1
	v_mfma_f32_16x16x32_bf16 v[54:57], v[156:159], v[188:191], v[54:57]
	v_mfma_f32_16x16x32_bf16 v[50:53], v[170:173], v[188:191], v[50:53]
	v_mfma_f32_16x16x32_bf16 v[38:41], v[156:159], v[196:199], v[38:41]
	v_mfma_f32_16x16x32_bf16 v[34:37], v[170:173], v[196:199], v[34:37]
	v_mfma_f32_16x16x32_bf16 v[22:25], v[156:159], v[204:207], v[22:25]
	v_mfma_f32_16x16x32_bf16 v[18:21], v[170:173], v[204:207], v[18:21]
	v_mfma_f32_16x16x32_bf16 v[6:9], v[156:159], v[222:225], v[6:9]
	v_mfma_f32_16x16x32_bf16 v[2:5], v[170:173], v[222:225], v[2:5]
	v_mfma_f32_16x16x32_bf16 v[54:57], v[166:169], v[192:195], v[54:57]
	v_mfma_f32_16x16x32_bf16 v[50:53], v[174:177], v[192:195], v[50:53]
	v_mfma_f32_16x16x32_bf16 v[38:41], v[166:169], v[200:203], v[38:41]
	v_mfma_f32_16x16x32_bf16 v[34:37], v[174:177], v[200:203], v[34:37]
	v_mfma_f32_16x16x32_bf16 v[22:25], v[166:169], v[218:221], v[22:25]
	v_mfma_f32_16x16x32_bf16 v[18:21], v[174:177], v[218:221], v[18:21]
	v_mfma_f32_16x16x32_bf16 v[6:9], v[166:169], v[226:229], v[6:9]
	v_mfma_f32_16x16x32_bf16 v[2:5], v[174:177], v[226:229], v[2:5]
	s_setprio 0
	s_barrier
	s_add_i32 s41, s41, 2
	s_add_u32 s0, s0, 0x100
	s_addc_u32 s1, s1, 0
	s_add_u32 s35, s35, 0x100
	s_addc_u32 s40, s40, 0
	s_cmp_gt_u32 s41, 29
	s_cbranch_scc0 .LBB0_846
	s_and_b64 vcc, exec, s[8:9]
	s_movk_i32 s40, 0x4000
	s_movk_i32 s41, 0x6000
	s_cbranch_vccz .LBB0_849
	s_barrier

.LBB0_959:
	s_add_u32 s3, s16, 0xfff80080
	s_addc_u32 s18, s17, -1
	s_add_i32 s42, 0, 0x10000
	s_cmp_eq_u32 s46, 28
	s_cselect_b32 s21, s11, s18
	s_cselect_b32 s20, s40, s3
	v_add_u32_e32 v140, s42, v143
	s_cselect_b32 s19, s9, s45
	s_cselect_b32 s18, s41, s44
	s_add_i32 s3, 0, 0x14000
	ds_read_b128 v[146:149], v140
	ds_read_b128 v[150:153], v140 offset:1024
	ds_read_b128 v[154:157], v140 offset:2048
	ds_read_b128 v[158:161], v140 offset:3072
	v_add_u32_e32 v140, s3, v143
	ds_read_b128 v[162:165], v140
	ds_read_b128 v[166:169], v140 offset:1024
	ds_read_b128 v[170:173], v140 offset:2048
	ds_read_b128 v[174:177], v140 offset:3072
	v_lshl_add_u64 v[140:141], s[16:17], 0, v[136:137]
	s_add_i32 m0, s25, 0xc000
	ds_read_b128 v[188:191], v145
	ds_read_b128 v[192:195], v145 offset:1024
	ds_read_b128 v[196:199], v145 offset:2048
	ds_read_b128 v[200:203], v145 offset:3072
	ds_read_b128 v[204:207], v145 offset:4096
	ds_read_b128 v[218:221], v145 offset:5120
	ds_read_b128 v[222:225], v145 offset:6144
	ds_read_b128 v[226:229], v145 offset:7168
	global_load_lds_dwordx4 v[140:141], off
	v_lshl_add_u64 v[140:141], s[16:17], 0, v[138:139]
	s_add_i32 m0, s25, 0xe000
	s_nop 0
	global_load_lds_dwordx4 v[140:141], off
	s_waitcnt vmcnt(8)
	s_waitcnt lgkmcnt(0)
	s_waitcnt lgkmcnt(0)
	v_mfma_f32_16x16x32_bf16 v[126:129], v[146:149], v[188:191], v[126:129]
	v_mfma_f32_16x16x32_bf16 v[122:125], v[154:157], v[188:191], v[122:125]
	s_barrier
	s_setprio 1
	v_mfma_f32_16x16x32_bf16 v[110:113], v[146:149], v[196:199], v[110:113]
	v_mfma_f32_16x16x32_bf16 v[106:109], v[154:157], v[196:199], v[106:109]
	v_mfma_f32_16x16x32_bf16 v[94:97], v[146:149], v[204:207], v[94:97]
	v_mfma_f32_16x16x32_bf16 v[90:93], v[154:157], v[204:207], v[90:93]
	v_mfma_f32_16x16x32_bf16 v[78:81], v[146:149], v[222:225], v[78:81]
	v_mfma_f32_16x16x32_bf16 v[74:77], v[154:157], v[222:225], v[74:77]
	v_mfma_f32_16x16x32_bf16 v[126:129], v[150:153], v[192:195], v[126:129]
	v_mfma_f32_16x16x32_bf16 v[122:125], v[158:161], v[192:195], v[122:125]
	v_mfma_f32_16x16x32_bf16 v[110:113], v[150:153], v[200:203], v[110:113]
	v_mfma_f32_16x16x32_bf16 v[106:109], v[158:161], v[200:203], v[106:109]
	v_mfma_f32_16x16x32_bf16 v[94:97], v[150:153], v[218:221], v[94:97]
	v_mfma_f32_16x16x32_bf16 v[90:93], v[158:161], v[218:221], v[90:93]
	v_mfma_f32_16x16x32_bf16 v[78:81], v[150:153], v[226:229], v[78:81]
	v_mfma_f32_16x16x32_bf16 v[74:77], v[158:161], v[226:229], v[74:77]
	s_setprio 0
	s_setprio 1
	v_mfma_f32_16x16x32_bf16 v[118:121], v[162:165], v[188:191], v[118:121]
	v_mfma_f32_16x16x32_bf16 v[114:117], v[170:173], v[188:191], v[114:117]
	v_mfma_f32_16x16x32_bf16 v[102:105], v[162:165], v[196:199], v[102:105]
	v_mfma_f32_16x16x32_bf16 v[98:101], v[170:173], v[196:199], v[98:101]
	v_mfma_f32_16x16x32_bf16 v[86:89], v[162:165], v[204:207], v[86:89]
	v_mfma_f32_16x16x32_bf16 v[82:85], v[170:173], v[204:207], v[82:85]
	v_mfma_f32_16x16x32_bf16 v[70:73], v[162:165], v[222:225], v[70:73]
	v_mfma_f32_16x16x32_bf16 v[66:69], v[170:173], v[222:225], v[66:69]
	v_mfma_f32_16x16x32_bf16 v[118:121], v[166:169], v[192:195], v[118:121]
	v_mfma_f32_16x16x32_bf16 v[114:117], v[174:177], v[192:195], v[114:117]
	v_mfma_f32_16x16x32_bf16 v[102:105], v[166:169], v[200:203], v[102:105]
	v_mfma_f32_16x16x32_bf16 v[98:101], v[174:177], v[200:203], v[98:101]
	v_mfma_f32_16x16x32_bf16 v[86:89], v[166:169], v[218:221], v[86:89]
	v_mfma_f32_16x16x32_bf16 v[82:85], v[174:177], v[218:221], v[82:85]
	v_mfma_f32_16x16x32_bf16 v[70:73], v[166:169], v[226:229], v[70:73]
	v_mfma_f32_16x16x32_bf16 v[66:69], v[174:177], v[226:229], v[66:69]
	s_setprio 0
	s_barrier
	s_add_i32 s42, s42, s24
	v_lshl_add_u64 v[140:141], s[18:19], 0, v[0:1]
	s_mov_b32 m0, s42
	ds_read_b128 v[188:191], v145 offset:16384
	ds_read_b128 v[192:195], v145 offset:17408
	ds_read_b128 v[196:199], v145 offset:18432
	ds_read_b128 v[200:203], v145 offset:19456
	ds_read_b128 v[204:207], v145 offset:20480
	ds_read_b128 v[218:221], v145 offset:21504
	ds_read_b128 v[222:225], v145 offset:22528
	ds_read_b128 v[226:229], v145 offset:23552
	global_load_lds_dwordx4 v[140:141], off
	s_add_i32 m0, s42, 0x2000
	s_add_u32 s56, s18, 0x80000
	v_lshl_add_u64 v[178:179], s[18:19], 0, v[130:131]
	s_addc_u32 s57, s19, 0
	s_add_i32 s3, s3, s24
	global_load_lds_dwordx4 v[178:179], off
	v_lshl_add_u64 v[180:181], s[56:57], 0, v[0:1]
	s_mov_b32 m0, s3
	v_lshl_add_u64 v[182:183], s[20:21], 0, v[132:133]
	global_load_lds_dwordx4 v[180:181], off
	v_lshl_add_u64 v[180:181], s[56:57], 0, v[130:131]
	s_add_i32 m0, s3, 0x2000
	s_nop 0
	global_load_lds_dwordx4 v[180:181], off
	v_lshl_add_u64 v[180:181], s[20:21], 0, v[134:135]
	s_mov_b32 m0, s25
	s_nop 0
	global_load_lds_dwordx4 v[180:181], off
	s_mov_b32 m0, s26
	s_nop 0
	global_load_lds_dwordx4 v[182:183], off
	s_waitcnt vmcnt(8)
	s_waitcnt lgkmcnt(0)
	s_waitcnt lgkmcnt(0)
	v_mfma_f32_16x16x32_bf16 v[62:65], v[146:149], v[188:191], v[62:65]
	v_mfma_f32_16x16x32_bf16 v[58:61], v[154:157], v[188:191], v[58:61]
	s_barrier
	s_setprio 1
	v_mfma_f32_16x16x32_bf16 v[46:49], v[146:149], v[196:199], v[46:49]
	v_mfma_f32_16x16x32_bf16 v[42:45], v[154:157], v[196:199], v[42:45]
	v_mfma_f32_16x16x32_bf16 v[30:33], v[146:149], v[204:207], v[30:33]
	v_mfma_f32_16x16x32_bf16 v[26:29], v[154:157], v[204:207], v[26:29]
	v_mfma_f32_16x16x32_bf16 v[14:17], v[146:149], v[222:225], v[14:17]
	v_mfma_f32_16x16x32_bf16 v[10:13], v[154:157], v[222:225], v[10:13]
	v_mfma_f32_16x16x32_bf16 v[62:65], v[150:153], v[192:195], v[62:65]
	v_mfma_f32_16x16x32_bf16 v[58:61], v[158:161], v[192:195], v[58:61]
	v_mfma_f32_16x16x32_bf16 v[46:49], v[150:153], v[200:203], v[46:49]
	v_mfma_f32_16x16x32_bf16 v[42:45], v[158:161], v[200:203], v[42:45]
	v_mfma_f32_16x16x32_bf16 v[30:33], v[150:153], v[218:221], v[30:33]
	v_mfma_f32_16x16x32_bf16 v[26:29], v[158:161], v[218:221], v[26:29]
	v_mfma_f32_16x16x32_bf16 v[14:17], v[150:153], v[226:229], v[14:17]
	v_mfma_f32_16x16x32_bf16 v[10:13], v[158:161], v[226:229], v[10:13]
	s_setprio 0
	s_setprio 1
	v_mfma_f32_16x16x32_bf16 v[54:57], v[162:165], v[188:191], v[54:57]
	v_mfma_f32_16x16x32_bf16 v[50:53], v[170:173], v[188:191], v[50:53]
	v_mfma_f32_16x16x32_bf16 v[38:41], v[162:165], v[196:199], v[38:41]
	v_mfma_f32_16x16x32_bf16 v[34:37], v[170:173], v[196:199], v[34:37]
	v_mfma_f32_16x16x32_bf16 v[22:25], v[162:165], v[204:207], v[22:25]
	v_mfma_f32_16x16x32_bf16 v[18:21], v[170:173], v[204:207], v[18:21]
	v_mfma_f32_16x16x32_bf16 v[6:9], v[162:165], v[222:225], v[6:9]
	v_mfma_f32_16x16x32_bf16 v[2:5], v[170:173], v[222:225], v[2:5]
	v_mfma_f32_16x16x32_bf16 v[54:57], v[166:169], v[192:195], v[54:57]
	v_mfma_f32_16x16x32_bf16 v[50:53], v[174:177], v[192:195], v[50:53]
	v_mfma_f32_16x16x32_bf16 v[38:41], v[166:169], v[200:203], v[38:41]
	v_mfma_f32_16x16x32_bf16 v[34:37], v[174:177], v[200:203], v[34:37]
	v_mfma_f32_16x16x32_bf16 v[22:25], v[166:169], v[218:221], v[22:25]
	v_mfma_f32_16x16x32_bf16 v[18:21], v[174:177], v[218:221], v[18:21]
	v_mfma_f32_16x16x32_bf16 v[6:9], v[166:169], v[226:229], v[6:9]
	v_mfma_f32_16x16x32_bf16 v[2:5], v[174:177], v[226:229], v[2:5]
	s_setprio 0
	s_barrier
	s_add_i32 s3, 0, 0x18000
	s_add_i32 s42, 0, 0x1c000
	v_add_u32_e32 v158, s3, v143
	v_add_u32_e32 v174, s42, v143
	ds_read_b128 v[146:149], v158
	ds_read_b128 v[150:153], v158 offset:1024
	ds_read_b128 v[154:157], v158 offset:2048
	ds_read_b128 v[158:161], v158 offset:3072
	ds_read_b128 v[162:165], v174
	ds_read_b128 v[166:169], v174 offset:1024
	ds_read_b128 v[170:173], v174 offset:2048
	ds_read_b128 v[174:177], v174 offset:3072
	s_add_u32 s20, s20, 0x80000
	s_addc_u32 s21, s21, 0
	s_mov_b32 m0, s27
	v_lshl_add_u64 v[184:185], s[20:21], 0, v[134:135]
	ds_read_b128 v[188:191], v145 offset:32768
	ds_read_b128 v[192:195], v145 offset:33792
	ds_read_b128 v[196:199], v145 offset:34816
	ds_read_b128 v[200:203], v145 offset:35840
	ds_read_b128 v[204:207], v145 offset:36864
	ds_read_b128 v[218:221], v145 offset:37888
	ds_read_b128 v[222:225], v145 offset:38912
	ds_read_b128 v[226:229], v145 offset:39936
	global_load_lds_dwordx4 v[184:185], off
	v_lshl_add_u64 v[184:185], s[20:21], 0, v[132:133]
	s_mov_b32 m0, s28
	s_nop 0
	global_load_lds_dwordx4 v[184:185], off
	s_waitcnt vmcnt(8)
	s_waitcnt lgkmcnt(0)
	s_waitcnt lgkmcnt(0)
	v_mfma_f32_16x16x32_bf16 v[126:129], v[146:149], v[188:191], v[126:129]
	v_mfma_f32_16x16x32_bf16 v[122:125], v[154:157], v[188:191], v[122:125]
	s_barrier
	s_setprio 1
	v_mfma_f32_16x16x32_bf16 v[110:113], v[146:149], v[196:199], v[110:113]
	v_mfma_f32_16x16x32_bf16 v[106:109], v[154:157], v[196:199], v[106:109]
	v_mfma_f32_16x16x32_bf16 v[94:97], v[146:149], v[204:207], v[94:97]
	v_mfma_f32_16x16x32_bf16 v[90:93], v[154:157], v[204:207], v[90:93]
	v_mfma_f32_16x16x32_bf16 v[78:81], v[146:149], v[222:225], v[78:81]
	v_mfma_f32_16x16x32_bf16 v[74:77], v[154:157], v[222:225], v[74:77]
	v_mfma_f32_16x16x32_bf16 v[126:129], v[150:153], v[192:195], v[126:129]
	v_mfma_f32_16x16x32_bf16 v[122:125], v[158:161], v[192:195], v[122:125]
	v_mfma_f32_16x16x32_bf16 v[110:113], v[150:153], v[200:203], v[110:113]
	v_mfma_f32_16x16x32_bf16 v[106:109], v[158:161], v[200:203], v[106:109]
	v_mfma_f32_16x16x32_bf16 v[94:97], v[150:153], v[218:221], v[94:97]
	v_mfma_f32_16x16x32_bf16 v[90:93], v[158:161], v[218:221], v[90:93]
	v_mfma_f32_16x16x32_bf16 v[78:81], v[150:153], v[226:229], v[78:81]
	v_mfma_f32_16x16x32_bf16 v[74:77], v[158:161], v[226:229], v[74:77]
	s_setprio 0
	s_setprio 1
	v_mfma_f32_16x16x32_bf16 v[118:121], v[162:165], v[188:191], v[118:121]
	v_mfma_f32_16x16x32_bf16 v[114:117], v[170:173], v[188:191], v[114:117]
	v_mfma_f32_16x16x32_bf16 v[102:105], v[162:165], v[196:199], v[102:105]
	v_mfma_f32_16x16x32_bf16 v[98:101], v[170:173], v[196:199], v[98:101]
	v_mfma_f32_16x16x32_bf16 v[86:89], v[162:165], v[204:207], v[86:89]
	v_mfma_f32_16x16x32_bf16 v[82:85], v[170:173], v[204:207], v[82:85]
	v_mfma_f32_16x16x32_bf16 v[70:73], v[162:165], v[222:225], v[70:73]
	v_mfma_f32_16x16x32_bf16 v[66:69], v[170:173], v[222:225], v[66:69]
	v_mfma_f32_16x16x32_bf16 v[118:121], v[166:169], v[192:195], v[118:121]
	v_mfma_f32_16x16x32_bf16 v[114:117], v[174:177], v[192:195], v[114:117]
	v_mfma_f32_16x16x32_bf16 v[102:105], v[166:169], v[200:203], v[102:105]
	v_mfma_f32_16x16x32_bf16 v[98:101], v[174:177], v[200:203], v[98:101]
	v_mfma_f32_16x16x32_bf16 v[86:89], v[166:169], v[218:221], v[86:89]
	v_mfma_f32_16x16x32_bf16 v[82:85], v[174:177], v[218:221], v[82:85]
	v_mfma_f32_16x16x32_bf16 v[70:73], v[166:169], v[226:229], v[70:73]
	v_mfma_f32_16x16x32_bf16 v[66:69], v[174:177], v[226:229], v[66:69]
	s_setprio 0
	s_barrier
	s_add_i32 s3, s3, s24
	v_lshl_add_u64 v[140:141], v[140:141], 0, s[52:53]
	s_mov_b32 m0, s3
	ds_read_b128 v[188:191], v145 offset:49152
	ds_read_b128 v[192:195], v145 offset:50176
	ds_read_b128 v[196:199], v145 offset:51200
	ds_read_b128 v[200:203], v145 offset:52224
	ds_read_b128 v[204:207], v145 offset:53248
	ds_read_b128 v[218:221], v145 offset:54272
	ds_read_b128 v[222:225], v145 offset:55296
	ds_read_b128 v[226:229], v145 offset:56320
	global_load_lds_dwordx4 v[140:141], off
	s_add_i32 m0, s3, 0x2000
	s_add_u32 s18, s18, 0x80080
	v_lshl_add_u64 v[140:141], v[178:179], 0, s[52:53]
	s_addc_u32 s19, s19, 0
	s_add_i32 s3, s42, s24
	global_load_lds_dwordx4 v[140:141], off
	v_lshl_add_u64 v[140:141], s[18:19], 0, v[0:1]
	s_mov_b32 m0, s3
	s_nop 0
	global_load_lds_dwordx4 v[140:141], off
	v_lshl_add_u64 v[140:141], s[18:19], 0, v[130:131]
	s_add_i32 m0, s3, 0x2000
	s_nop 0
	global_load_lds_dwordx4 v[140:141], off
	v_lshl_add_u64 v[140:141], v[180:181], 0, s[52:53]
	s_mov_b32 m0, s29
	s_nop 0
	global_load_lds_dwordx4 v[140:141], off
	v_lshl_add_u64 v[140:141], v[182:183], 0, s[52:53]
	s_mov_b32 m0, s30
	s_nop 0
	global_load_lds_dwordx4 v[140:141], off
	s_waitcnt vmcnt(8)
	s_waitcnt lgkmcnt(0)
	s_waitcnt lgkmcnt(0)
	v_mfma_f32_16x16x32_bf16 v[62:65], v[146:149], v[188:191], v[62:65]
	v_mfma_f32_16x16x32_bf16 v[58:61], v[154:157], v[188:191], v[58:61]
	s_barrier
	s_setprio 1
	v_mfma_f32_16x16x32_bf16 v[46:49], v[146:149], v[196:199], v[46:49]
	v_mfma_f32_16x16x32_bf16 v[42:45], v[154:157], v[196:199], v[42:45]
	v_mfma_f32_16x16x32_bf16 v[30:33], v[146:149], v[204:207], v[30:33]
	v_mfma_f32_16x16x32_bf16 v[26:29], v[154:157], v[204:207], v[26:29]
	v_mfma_f32_16x16x32_bf16 v[14:17], v[146:149], v[222:225], v[14:17]
	v_mfma_f32_16x16x32_bf16 v[10:13], v[154:157], v[222:225], v[10:13]
	v_mfma_f32_16x16x32_bf16 v[62:65], v[150:153], v[192:195], v[62:65]
	v_mfma_f32_16x16x32_bf16 v[58:61], v[158:161], v[192:195], v[58:61]
	v_mfma_f32_16x16x32_bf16 v[46:49], v[150:153], v[200:203], v[46:49]
	v_mfma_f32_16x16x32_bf16 v[42:45], v[158:161], v[200:203], v[42:45]
	v_mfma_f32_16x16x32_bf16 v[30:33], v[150:153], v[218:221], v[30:33]
	v_mfma_f32_16x16x32_bf16 v[26:29], v[158:161], v[218:221], v[26:29]
	v_mfma_f32_16x16x32_bf16 v[14:17], v[150:153], v[226:229], v[14:17]
	v_mfma_f32_16x16x32_bf16 v[10:13], v[158:161], v[226:229], v[10:13]
	s_setprio 0
	s_setprio 1
	v_mfma_f32_16x16x32_bf16 v[54:57], v[162:165], v[188:191], v[54:57]
	v_mfma_f32_16x16x32_bf16 v[50:53], v[170:173], v[188:191], v[50:53]
	v_mfma_f32_16x16x32_bf16 v[38:41], v[162:165], v[196:199], v[38:41]
	v_mfma_f32_16x16x32_bf16 v[34:37], v[170:173], v[196:199], v[34:37]
	v_mfma_f32_16x16x32_bf16 v[22:25], v[162:165], v[204:207], v[22:25]
	v_mfma_f32_16x16x32_bf16 v[18:21], v[170:173], v[204:207], v[18:21]
	v_mfma_f32_16x16x32_bf16 v[6:9], v[162:165], v[222:225], v[6:9]
	v_mfma_f32_16x16x32_bf16 v[2:5], v[170:173], v[222:225], v[2:5]
	v_mfma_f32_16x16x32_bf16 v[54:57], v[166:169], v[192:195], v[54:57]
	v_mfma_f32_16x16x32_bf16 v[50:53], v[174:177], v[192:195], v[50:53]
	v_mfma_f32_16x16x32_bf16 v[38:41], v[166:169], v[200:203], v[38:41]
	v_mfma_f32_16x16x32_bf16 v[34:37], v[174:177], v[200:203], v[34:37]
	v_mfma_f32_16x16x32_bf16 v[22:25], v[166:169], v[218:221], v[22:25]
	v_mfma_f32_16x16x32_bf16 v[18:21], v[174:177], v[218:221], v[18:21]
	v_mfma_f32_16x16x32_bf16 v[6:9], v[166:169], v[226:229], v[6:9]
	v_mfma_f32_16x16x32_bf16 v[2:5], v[174:177], v[226:229], v[2:5]
	s_setprio 0
	s_barrier
	s_add_i32 s46, s46, 2
	s_add_u32 s16, s16, 0x100
	s_addc_u32 s17, s17, 0
	s_add_u32 s44, s44, 0x100
	s_addc_u32 s45, s45, 0
	s_cmp_gt_u32 s46, 29
	s_cbranch_scc0 .LBB0_959
	s_and_b64 vcc, exec, s[6:7]
	s_movk_i32 s40, 0x4000
	s_movk_i32 s41, 0x6000
	s_mov_b32 s44, 0x8000
	s_mov_b32 s45, 0xa000
	s_cbranch_vccz .LBB0_962
	s_barrier

.LBB0_1024:
	s_add_u32 s3, s20, 0xffe00080
	s_addc_u32 s22, s21, -1
	s_add_i32 s42, 0, 0x10000
	s_cmpk_eq_i32 s57, 0x7c
	s_cselect_b32 s25, s15, s22
	s_cselect_b32 s24, s45, s3
	s_cselect_b32 s23, s13, s56
	s_cselect_b32 s22, s46, s47
	s_add_i32 s3, 0, 0x14000
	v_add_u32_e32 v152, s42, v163
	v_add_u32_e32 v160, s3, v163
	ds_read_b128 v[140:143], v152
	ds_read_b128 v[144:147], v152 offset:1024
	ds_read_b128 v[148:151], v152 offset:2048
	ds_read_b128 v[152:155], v152 offset:3072
	ds_read_b128 v[156:159], v160
	ds_read_b128 v[166:169], v160 offset:1024
	ds_read_b128 v[170:173], v160 offset:2048
	ds_read_b128 v[174:177], v160 offset:3072
	v_lshl_add_u64 v[160:161], s[20:21], 0, v[136:137]
	s_add_i32 m0, s28, 0xc000
	ds_read_b128 v[188:191], v165
	ds_read_b128 v[192:195], v165 offset:1024
	ds_read_b128 v[196:199], v165 offset:2048
	ds_read_b128 v[200:203], v165 offset:3072
	ds_read_b128 v[204:207], v165 offset:4096
	ds_read_b128 v[218:221], v165 offset:5120
	ds_read_b128 v[222:225], v165 offset:6144
	ds_read_b128 v[226:229], v165 offset:7168
	global_load_lds_dwordx4 v[160:161], off
	v_lshl_add_u64 v[160:161], s[20:21], 0, v[138:139]
	s_add_i32 m0, s28, 0xe000
	s_nop 0
	global_load_lds_dwordx4 v[160:161], off
	s_waitcnt vmcnt(8)
	s_waitcnt lgkmcnt(0)
	s_waitcnt lgkmcnt(0)
	v_mfma_f32_16x16x32_bf16 v[126:129], v[140:143], v[188:191], v[126:129]
	v_mfma_f32_16x16x32_bf16 v[122:125], v[148:151], v[188:191], v[122:125]
	s_barrier
	s_setprio 1
	v_mfma_f32_16x16x32_bf16 v[110:113], v[140:143], v[196:199], v[110:113]
	v_mfma_f32_16x16x32_bf16 v[106:109], v[148:151], v[196:199], v[106:109]
	v_mfma_f32_16x16x32_bf16 v[94:97], v[140:143], v[204:207], v[94:97]
	v_mfma_f32_16x16x32_bf16 v[90:93], v[148:151], v[204:207], v[90:93]
	v_mfma_f32_16x16x32_bf16 v[78:81], v[140:143], v[222:225], v[78:81]
	v_mfma_f32_16x16x32_bf16 v[74:77], v[148:151], v[222:225], v[74:77]
	v_mfma_f32_16x16x32_bf16 v[126:129], v[144:147], v[192:195], v[126:129]
	v_mfma_f32_16x16x32_bf16 v[122:125], v[152:155], v[192:195], v[122:125]
	v_mfma_f32_16x16x32_bf16 v[110:113], v[144:147], v[200:203], v[110:113]
	v_mfma_f32_16x16x32_bf16 v[106:109], v[152:155], v[200:203], v[106:109]
	v_mfma_f32_16x16x32_bf16 v[94:97], v[144:147], v[218:221], v[94:97]
	v_mfma_f32_16x16x32_bf16 v[90:93], v[152:155], v[218:221], v[90:93]
	v_mfma_f32_16x16x32_bf16 v[78:81], v[144:147], v[226:229], v[78:81]
	v_mfma_f32_16x16x32_bf16 v[74:77], v[152:155], v[226:229], v[74:77]
	s_setprio 0
	s_setprio 1
	v_mfma_f32_16x16x32_bf16 v[118:121], v[156:159], v[188:191], v[118:121]
	v_mfma_f32_16x16x32_bf16 v[114:117], v[170:173], v[188:191], v[114:117]
	v_mfma_f32_16x16x32_bf16 v[102:105], v[156:159], v[196:199], v[102:105]
	v_mfma_f32_16x16x32_bf16 v[98:101], v[170:173], v[196:199], v[98:101]
	v_mfma_f32_16x16x32_bf16 v[86:89], v[156:159], v[204:207], v[86:89]
	v_mfma_f32_16x16x32_bf16 v[82:85], v[170:173], v[204:207], v[82:85]
	v_mfma_f32_16x16x32_bf16 v[70:73], v[156:159], v[222:225], v[70:73]
	v_mfma_f32_16x16x32_bf16 v[66:69], v[170:173], v[222:225], v[66:69]
	v_mfma_f32_16x16x32_bf16 v[118:121], v[166:169], v[192:195], v[118:121]
	v_mfma_f32_16x16x32_bf16 v[114:117], v[174:177], v[192:195], v[114:117]
	v_mfma_f32_16x16x32_bf16 v[102:105], v[166:169], v[200:203], v[102:105]
	v_mfma_f32_16x16x32_bf16 v[98:101], v[174:177], v[200:203], v[98:101]
	v_mfma_f32_16x16x32_bf16 v[86:89], v[166:169], v[218:221], v[86:89]
	v_mfma_f32_16x16x32_bf16 v[82:85], v[174:177], v[218:221], v[82:85]
	v_mfma_f32_16x16x32_bf16 v[70:73], v[166:169], v[226:229], v[70:73]
	v_mfma_f32_16x16x32_bf16 v[66:69], v[174:177], v[226:229], v[66:69]
	s_setprio 0
	s_barrier
	s_add_i32 s42, s42, s27
	v_lshl_add_u64 v[160:161], s[22:23], 0, v[0:1]
	s_mov_b32 m0, s42
	ds_read_b128 v[188:191], v165 offset:16384
	ds_read_b128 v[192:195], v165 offset:17408
	ds_read_b128 v[196:199], v165 offset:18432
	ds_read_b128 v[200:203], v165 offset:19456
	ds_read_b128 v[204:207], v165 offset:20480
	ds_read_b128 v[218:221], v165 offset:21504
	ds_read_b128 v[222:225], v165 offset:22528
	ds_read_b128 v[226:229], v165 offset:23552
	global_load_lds_dwordx4 v[160:161], off
	s_add_i32 m0, s42, 0x2000
	s_add_u32 s58, s22, 0x200000
	v_lshl_add_u64 v[178:179], s[22:23], 0, v[130:131]
	s_addc_u32 s59, s23, 0
	s_add_i32 s3, s3, s27
	global_load_lds_dwordx4 v[178:179], off
	v_lshl_add_u64 v[180:181], s[58:59], 0, v[0:1]
	s_mov_b32 m0, s3
	v_lshl_add_u64 v[182:183], s[24:25], 0, v[132:133]
	global_load_lds_dwordx4 v[180:181], off
	v_lshl_add_u64 v[180:181], s[58:59], 0, v[130:131]
	s_add_i32 m0, s3, 0x2000
	s_nop 0
	global_load_lds_dwordx4 v[180:181], off
	v_lshl_add_u64 v[180:181], s[24:25], 0, v[134:135]
	s_mov_b32 m0, s28
	s_nop 0
	global_load_lds_dwordx4 v[180:181], off
	s_mov_b32 m0, s29
	s_nop 0
	global_load_lds_dwordx4 v[182:183], off
	s_waitcnt vmcnt(8)
	s_waitcnt lgkmcnt(0)
	s_waitcnt lgkmcnt(0)
	v_mfma_f32_16x16x32_bf16 v[62:65], v[140:143], v[188:191], v[62:65]
	v_mfma_f32_16x16x32_bf16 v[58:61], v[148:151], v[188:191], v[58:61]
	s_barrier
	s_setprio 1
	v_mfma_f32_16x16x32_bf16 v[46:49], v[140:143], v[196:199], v[46:49]
	v_mfma_f32_16x16x32_bf16 v[42:45], v[148:151], v[196:199], v[42:45]
	v_mfma_f32_16x16x32_bf16 v[30:33], v[140:143], v[204:207], v[30:33]
	v_mfma_f32_16x16x32_bf16 v[26:29], v[148:151], v[204:207], v[26:29]
	v_mfma_f32_16x16x32_bf16 v[14:17], v[140:143], v[222:225], v[14:17]
	v_mfma_f32_16x16x32_bf16 v[10:13], v[148:151], v[222:225], v[10:13]
	v_mfma_f32_16x16x32_bf16 v[62:65], v[144:147], v[192:195], v[62:65]
	v_mfma_f32_16x16x32_bf16 v[58:61], v[152:155], v[192:195], v[58:61]
	v_mfma_f32_16x16x32_bf16 v[46:49], v[144:147], v[200:203], v[46:49]
	v_mfma_f32_16x16x32_bf16 v[42:45], v[152:155], v[200:203], v[42:45]
	v_mfma_f32_16x16x32_bf16 v[30:33], v[144:147], v[218:221], v[30:33]
	v_mfma_f32_16x16x32_bf16 v[26:29], v[152:155], v[218:221], v[26:29]
	v_mfma_f32_16x16x32_bf16 v[14:17], v[144:147], v[226:229], v[14:17]
	v_mfma_f32_16x16x32_bf16 v[10:13], v[152:155], v[226:229], v[10:13]
	s_setprio 0
	s_setprio 1
	v_mfma_f32_16x16x32_bf16 v[54:57], v[156:159], v[188:191], v[54:57]
	v_mfma_f32_16x16x32_bf16 v[50:53], v[170:173], v[188:191], v[50:53]
	v_mfma_f32_16x16x32_bf16 v[38:41], v[156:159], v[196:199], v[38:41]
	v_mfma_f32_16x16x32_bf16 v[34:37], v[170:173], v[196:199], v[34:37]
	v_mfma_f32_16x16x32_bf16 v[22:25], v[156:159], v[204:207], v[22:25]
	v_mfma_f32_16x16x32_bf16 v[18:21], v[170:173], v[204:207], v[18:21]
	v_mfma_f32_16x16x32_bf16 v[6:9], v[156:159], v[222:225], v[6:9]
	v_mfma_f32_16x16x32_bf16 v[2:5], v[170:173], v[222:225], v[2:5]
	v_mfma_f32_16x16x32_bf16 v[54:57], v[166:169], v[192:195], v[54:57]
	v_mfma_f32_16x16x32_bf16 v[50:53], v[174:177], v[192:195], v[50:53]
	v_mfma_f32_16x16x32_bf16 v[38:41], v[166:169], v[200:203], v[38:41]
	v_mfma_f32_16x16x32_bf16 v[34:37], v[174:177], v[200:203], v[34:37]
	v_mfma_f32_16x16x32_bf16 v[22:25], v[166:169], v[218:221], v[22:25]
	v_mfma_f32_16x16x32_bf16 v[18:21], v[174:177], v[218:221], v[18:21]
	v_mfma_f32_16x16x32_bf16 v[6:9], v[166:169], v[226:229], v[6:9]
	v_mfma_f32_16x16x32_bf16 v[2:5], v[174:177], v[226:229], v[2:5]
	s_setprio 0
	s_barrier
	s_add_i32 s3, 0, 0x18000
	s_add_i32 s42, 0, 0x1c000
	v_add_u32_e32 v152, s3, v163
	v_add_u32_e32 v174, s42, v163
	ds_read_b128 v[140:143], v152
	ds_read_b128 v[144:147], v152 offset:1024
	ds_read_b128 v[148:151], v152 offset:2048
	ds_read_b128 v[152:155], v152 offset:3072
	ds_read_b128 v[156:159], v174
	ds_read_b128 v[166:169], v174 offset:1024
	ds_read_b128 v[170:173], v174 offset:2048
	ds_read_b128 v[174:177], v174 offset:3072
	s_add_u32 s24, s24, 0x200000
	s_addc_u32 s25, s25, 0
	s_mov_b32 m0, s30
	v_lshl_add_u64 v[184:185], s[24:25], 0, v[134:135]
	ds_read_b128 v[188:191], v165 offset:32768
	ds_read_b128 v[192:195], v165 offset:33792
	ds_read_b128 v[196:199], v165 offset:34816
	ds_read_b128 v[200:203], v165 offset:35840
	ds_read_b128 v[204:207], v165 offset:36864
	ds_read_b128 v[218:221], v165 offset:37888
	ds_read_b128 v[222:225], v165 offset:38912
	ds_read_b128 v[226:229], v165 offset:39936
	global_load_lds_dwordx4 v[184:185], off
	v_lshl_add_u64 v[184:185], s[24:25], 0, v[132:133]
	s_mov_b32 m0, s31
	s_nop 0
	global_load_lds_dwordx4 v[184:185], off
	s_waitcnt vmcnt(8)
	s_waitcnt lgkmcnt(0)
	s_waitcnt lgkmcnt(0)
	v_mfma_f32_16x16x32_bf16 v[126:129], v[140:143], v[188:191], v[126:129]
	v_mfma_f32_16x16x32_bf16 v[122:125], v[148:151], v[188:191], v[122:125]
	s_barrier
	s_setprio 1
	v_mfma_f32_16x16x32_bf16 v[110:113], v[140:143], v[196:199], v[110:113]
	v_mfma_f32_16x16x32_bf16 v[106:109], v[148:151], v[196:199], v[106:109]
	v_mfma_f32_16x16x32_bf16 v[94:97], v[140:143], v[204:207], v[94:97]
	v_mfma_f32_16x16x32_bf16 v[90:93], v[148:151], v[204:207], v[90:93]
	v_mfma_f32_16x16x32_bf16 v[78:81], v[140:143], v[222:225], v[78:81]
	v_mfma_f32_16x16x32_bf16 v[74:77], v[148:151], v[222:225], v[74:77]
	v_mfma_f32_16x16x32_bf16 v[126:129], v[144:147], v[192:195], v[126:129]
	v_mfma_f32_16x16x32_bf16 v[122:125], v[152:155], v[192:195], v[122:125]
	v_mfma_f32_16x16x32_bf16 v[110:113], v[144:147], v[200:203], v[110:113]
	v_mfma_f32_16x16x32_bf16 v[106:109], v[152:155], v[200:203], v[106:109]
	v_mfma_f32_16x16x32_bf16 v[94:97], v[144:147], v[218:221], v[94:97]
	v_mfma_f32_16x16x32_bf16 v[90:93], v[152:155], v[218:221], v[90:93]
	v_mfma_f32_16x16x32_bf16 v[78:81], v[144:147], v[226:229], v[78:81]
	v_mfma_f32_16x16x32_bf16 v[74:77], v[152:155], v[226:229], v[74:77]
	s_setprio 0
	s_setprio 1
	v_mfma_f32_16x16x32_bf16 v[118:121], v[156:159], v[188:191], v[118:121]
	v_mfma_f32_16x16x32_bf16 v[114:117], v[170:173], v[188:191], v[114:117]
	v_mfma_f32_16x16x32_bf16 v[102:105], v[156:159], v[196:199], v[102:105]
	v_mfma_f32_16x16x32_bf16 v[98:101], v[170:173], v[196:199], v[98:101]
	v_mfma_f32_16x16x32_bf16 v[86:89], v[156:159], v[204:207], v[86:89]
	v_mfma_f32_16x16x32_bf16 v[82:85], v[170:173], v[204:207], v[82:85]
	v_mfma_f32_16x16x32_bf16 v[70:73], v[156:159], v[222:225], v[70:73]
	v_mfma_f32_16x16x32_bf16 v[66:69], v[170:173], v[222:225], v[66:69]
	v_mfma_f32_16x16x32_bf16 v[118:121], v[166:169], v[192:195], v[118:121]
	v_mfma_f32_16x16x32_bf16 v[114:117], v[174:177], v[192:195], v[114:117]
	v_mfma_f32_16x16x32_bf16 v[102:105], v[166:169], v[200:203], v[102:105]
	v_mfma_f32_16x16x32_bf16 v[98:101], v[174:177], v[200:203], v[98:101]
	v_mfma_f32_16x16x32_bf16 v[86:89], v[166:169], v[218:221], v[86:89]
	v_mfma_f32_16x16x32_bf16 v[82:85], v[174:177], v[218:221], v[82:85]
	v_mfma_f32_16x16x32_bf16 v[70:73], v[166:169], v[226:229], v[70:73]
	v_mfma_f32_16x16x32_bf16 v[66:69], v[174:177], v[226:229], v[66:69]
	s_setprio 0
	s_barrier
	s_add_i32 s3, s3, s27
	v_lshl_add_u64 v[160:161], v[160:161], 0, s[52:53]
	s_mov_b32 m0, s3
	ds_read_b128 v[188:191], v165 offset:49152
	ds_read_b128 v[192:195], v165 offset:50176
	ds_read_b128 v[196:199], v165 offset:51200
	ds_read_b128 v[200:203], v165 offset:52224
	ds_read_b128 v[204:207], v165 offset:53248
	ds_read_b128 v[218:221], v165 offset:54272
	ds_read_b128 v[222:225], v165 offset:55296
	ds_read_b128 v[226:229], v165 offset:56320
	global_load_lds_dwordx4 v[160:161], off
	s_add_i32 m0, s3, 0x2000
	s_add_u32 s22, s22, 0x200080
	v_lshl_add_u64 v[160:161], v[178:179], 0, s[52:53]
	s_addc_u32 s23, s23, 0
	s_add_i32 s3, s42, s27
	global_load_lds_dwordx4 v[160:161], off
	v_lshl_add_u64 v[160:161], s[22:23], 0, v[0:1]
	s_mov_b32 m0, s3
	s_nop 0
	global_load_lds_dwordx4 v[160:161], off
	v_lshl_add_u64 v[160:161], s[22:23], 0, v[130:131]
	s_add_i32 m0, s3, 0x2000
	s_nop 0
	global_load_lds_dwordx4 v[160:161], off
	v_lshl_add_u64 v[160:161], v[180:181], 0, s[52:53]
	s_mov_b32 m0, s34
	s_nop 0
	global_load_lds_dwordx4 v[160:161], off
	v_lshl_add_u64 v[160:161], v[182:183], 0, s[52:53]
	s_mov_b32 m0, s35
	s_nop 0
	global_load_lds_dwordx4 v[160:161], off
	s_waitcnt vmcnt(8)
	s_waitcnt lgkmcnt(0)
	s_waitcnt lgkmcnt(0)
	v_mfma_f32_16x16x32_bf16 v[62:65], v[140:143], v[188:191], v[62:65]
	v_mfma_f32_16x16x32_bf16 v[58:61], v[148:151], v[188:191], v[58:61]
	s_barrier
	s_setprio 1
	v_mfma_f32_16x16x32_bf16 v[46:49], v[140:143], v[196:199], v[46:49]
	v_mfma_f32_16x16x32_bf16 v[42:45], v[148:151], v[196:199], v[42:45]
	v_mfma_f32_16x16x32_bf16 v[30:33], v[140:143], v[204:207], v[30:33]
	v_mfma_f32_16x16x32_bf16 v[26:29], v[148:151], v[204:207], v[26:29]
	v_mfma_f32_16x16x32_bf16 v[14:17], v[140:143], v[222:225], v[14:17]
	v_mfma_f32_16x16x32_bf16 v[10:13], v[148:151], v[222:225], v[10:13]
	v_mfma_f32_16x16x32_bf16 v[62:65], v[144:147], v[192:195], v[62:65]
	v_mfma_f32_16x16x32_bf16 v[58:61], v[152:155], v[192:195], v[58:61]
	v_mfma_f32_16x16x32_bf16 v[46:49], v[144:147], v[200:203], v[46:49]
	v_mfma_f32_16x16x32_bf16 v[42:45], v[152:155], v[200:203], v[42:45]
	v_mfma_f32_16x16x32_bf16 v[30:33], v[144:147], v[218:221], v[30:33]
	v_mfma_f32_16x16x32_bf16 v[26:29], v[152:155], v[218:221], v[26:29]
	v_mfma_f32_16x16x32_bf16 v[14:17], v[144:147], v[226:229], v[14:17]
	v_mfma_f32_16x16x32_bf16 v[10:13], v[152:155], v[226:229], v[10:13]
	s_setprio 0
	s_setprio 1
	v_mfma_f32_16x16x32_bf16 v[54:57], v[156:159], v[188:191], v[54:57]
	v_mfma_f32_16x16x32_bf16 v[50:53], v[170:173], v[188:191], v[50:53]
	v_mfma_f32_16x16x32_bf16 v[38:41], v[156:159], v[196:199], v[38:41]
	v_mfma_f32_16x16x32_bf16 v[34:37], v[170:173], v[196:199], v[34:37]
	v_mfma_f32_16x16x32_bf16 v[22:25], v[156:159], v[204:207], v[22:25]
	v_mfma_f32_16x16x32_bf16 v[18:21], v[170:173], v[204:207], v[18:21]
	v_mfma_f32_16x16x32_bf16 v[6:9], v[156:159], v[222:225], v[6:9]
	v_mfma_f32_16x16x32_bf16 v[2:5], v[170:173], v[222:225], v[2:5]
	v_mfma_f32_16x16x32_bf16 v[54:57], v[166:169], v[192:195], v[54:57]
	v_mfma_f32_16x16x32_bf16 v[50:53], v[174:177], v[192:195], v[50:53]
	v_mfma_f32_16x16x32_bf16 v[38:41], v[166:169], v[200:203], v[38:41]
	v_mfma_f32_16x16x32_bf16 v[34:37], v[174:177], v[200:203], v[34:37]
	v_mfma_f32_16x16x32_bf16 v[22:25], v[166:169], v[218:221], v[22:25]
	v_mfma_f32_16x16x32_bf16 v[18:21], v[174:177], v[218:221], v[18:21]
	v_mfma_f32_16x16x32_bf16 v[6:9], v[166:169], v[226:229], v[6:9]
	v_mfma_f32_16x16x32_bf16 v[2:5], v[174:177], v[226:229], v[2:5]
	s_setprio 0
	s_barrier
	s_add_i32 s57, s57, 2
	s_add_u32 s20, s20, 0x100
	s_addc_u32 s21, s21, 0
	s_add_u32 s47, s47, 0x100
	s_addc_u32 s56, s56, 0
	s_cmpk_gt_u32 s57, 0x7d
	s_cbranch_scc0 .LBB0_1024
	s_and_b64 vcc, exec, s[10:11]
	s_mov_b32 s45, 0xa000
	s_cbranch_vccz .LBB0_1027
	s_barrier

.LBB0_1046:
	s_add_u32 s3, s18, 0xffe00080
	s_addc_u32 s20, s19, -1
	s_add_i32 s42, 0, 0x10000
	s_cmpk_eq_i32 s47, 0x7c
	s_cselect_b32 s23, s13, s20
	s_cselect_b32 s22, s41, s3
	s_cselect_b32 s21, s11, s46
	s_cselect_b32 s20, s44, s45
	s_add_i32 s3, 0, 0x14000
	v_add_u32_e32 v152, s42, v163
	v_add_u32_e32 v160, s3, v163
	ds_read_b128 v[140:143], v152
	ds_read_b128 v[144:147], v152 offset:1024
	ds_read_b128 v[148:151], v152 offset:2048
	ds_read_b128 v[152:155], v152 offset:3072
	ds_read_b128 v[156:159], v160
	ds_read_b128 v[166:169], v160 offset:1024
	ds_read_b128 v[170:173], v160 offset:2048
	ds_read_b128 v[174:177], v160 offset:3072
	v_lshl_add_u64 v[160:161], s[18:19], 0, v[136:137]
	s_add_i32 m0, s25, 0xc000
	ds_read_b128 v[188:191], v165
	ds_read_b128 v[192:195], v165 offset:1024
	ds_read_b128 v[196:199], v165 offset:2048
	ds_read_b128 v[200:203], v165 offset:3072
	ds_read_b128 v[204:207], v165 offset:4096
	ds_read_b128 v[218:221], v165 offset:5120
	ds_read_b128 v[222:225], v165 offset:6144
	ds_read_b128 v[226:229], v165 offset:7168
	global_load_lds_dwordx4 v[160:161], off
	v_lshl_add_u64 v[160:161], s[18:19], 0, v[138:139]
	s_add_i32 m0, s25, 0xe000
	s_nop 0
	global_load_lds_dwordx4 v[160:161], off
	s_waitcnt vmcnt(8)
	s_waitcnt lgkmcnt(0)
	s_waitcnt lgkmcnt(0)
	v_mfma_f32_16x16x32_bf16 v[126:129], v[140:143], v[188:191], v[126:129]
	v_mfma_f32_16x16x32_bf16 v[122:125], v[148:151], v[188:191], v[122:125]
	s_barrier
	s_setprio 1
	v_mfma_f32_16x16x32_bf16 v[110:113], v[140:143], v[196:199], v[110:113]
	v_mfma_f32_16x16x32_bf16 v[106:109], v[148:151], v[196:199], v[106:109]
	v_mfma_f32_16x16x32_bf16 v[94:97], v[140:143], v[204:207], v[94:97]
	v_mfma_f32_16x16x32_bf16 v[90:93], v[148:151], v[204:207], v[90:93]
	v_mfma_f32_16x16x32_bf16 v[78:81], v[140:143], v[222:225], v[78:81]
	v_mfma_f32_16x16x32_bf16 v[74:77], v[148:151], v[222:225], v[74:77]
	v_mfma_f32_16x16x32_bf16 v[126:129], v[144:147], v[192:195], v[126:129]
	v_mfma_f32_16x16x32_bf16 v[122:125], v[152:155], v[192:195], v[122:125]
	v_mfma_f32_16x16x32_bf16 v[110:113], v[144:147], v[200:203], v[110:113]
	v_mfma_f32_16x16x32_bf16 v[106:109], v[152:155], v[200:203], v[106:109]
	v_mfma_f32_16x16x32_bf16 v[94:97], v[144:147], v[218:221], v[94:97]
	v_mfma_f32_16x16x32_bf16 v[90:93], v[152:155], v[218:221], v[90:93]
	v_mfma_f32_16x16x32_bf16 v[78:81], v[144:147], v[226:229], v[78:81]
	v_mfma_f32_16x16x32_bf16 v[74:77], v[152:155], v[226:229], v[74:77]
	s_setprio 0
	s_setprio 1
	v_mfma_f32_16x16x32_bf16 v[118:121], v[156:159], v[188:191], v[118:121]
	v_mfma_f32_16x16x32_bf16 v[114:117], v[170:173], v[188:191], v[114:117]
	v_mfma_f32_16x16x32_bf16 v[102:105], v[156:159], v[196:199], v[102:105]
	v_mfma_f32_16x16x32_bf16 v[98:101], v[170:173], v[196:199], v[98:101]
	v_mfma_f32_16x16x32_bf16 v[86:89], v[156:159], v[204:207], v[86:89]
	v_mfma_f32_16x16x32_bf16 v[82:85], v[170:173], v[204:207], v[82:85]
	v_mfma_f32_16x16x32_bf16 v[70:73], v[156:159], v[222:225], v[70:73]
	v_mfma_f32_16x16x32_bf16 v[66:69], v[170:173], v[222:225], v[66:69]
	v_mfma_f32_16x16x32_bf16 v[118:121], v[166:169], v[192:195], v[118:121]
	v_mfma_f32_16x16x32_bf16 v[114:117], v[174:177], v[192:195], v[114:117]
	v_mfma_f32_16x16x32_bf16 v[102:105], v[166:169], v[200:203], v[102:105]
	v_mfma_f32_16x16x32_bf16 v[98:101], v[174:177], v[200:203], v[98:101]
	v_mfma_f32_16x16x32_bf16 v[86:89], v[166:169], v[218:221], v[86:89]
	v_mfma_f32_16x16x32_bf16 v[82:85], v[174:177], v[218:221], v[82:85]
	v_mfma_f32_16x16x32_bf16 v[70:73], v[166:169], v[226:229], v[70:73]
	v_mfma_f32_16x16x32_bf16 v[66:69], v[174:177], v[226:229], v[66:69]
	s_setprio 0
	s_barrier
	s_add_i32 s42, s42, s24
	v_lshl_add_u64 v[160:161], s[20:21], 0, v[0:1]
	s_mov_b32 m0, s42
	ds_read_b128 v[188:191], v165 offset:16384
	ds_read_b128 v[192:195], v165 offset:17408
	ds_read_b128 v[196:199], v165 offset:18432
	ds_read_b128 v[200:203], v165 offset:19456
	ds_read_b128 v[204:207], v165 offset:20480
	ds_read_b128 v[218:221], v165 offset:21504
	ds_read_b128 v[222:225], v165 offset:22528
	ds_read_b128 v[226:229], v165 offset:23552
	global_load_lds_dwordx4 v[160:161], off
	s_add_i32 m0, s42, 0x2000
	s_add_u32 s56, s20, 0x200000
	v_lshl_add_u64 v[178:179], s[20:21], 0, v[130:131]
	s_addc_u32 s57, s21, 0
	s_add_i32 s3, s3, s24
	global_load_lds_dwordx4 v[178:179], off
	v_lshl_add_u64 v[180:181], s[56:57], 0, v[0:1]
	s_mov_b32 m0, s3
	v_lshl_add_u64 v[182:183], s[22:23], 0, v[132:133]
	global_load_lds_dwordx4 v[180:181], off
	v_lshl_add_u64 v[180:181], s[56:57], 0, v[130:131]
	s_add_i32 m0, s3, 0x2000
	s_nop 0
	global_load_lds_dwordx4 v[180:181], off
	v_lshl_add_u64 v[180:181], s[22:23], 0, v[134:135]
	s_mov_b32 m0, s25
	s_nop 0
	global_load_lds_dwordx4 v[180:181], off
	s_mov_b32 m0, s27
	s_nop 0
	global_load_lds_dwordx4 v[182:183], off
	s_waitcnt vmcnt(8)
	s_waitcnt lgkmcnt(0)
	s_waitcnt lgkmcnt(0)
	v_mfma_f32_16x16x32_bf16 v[62:65], v[140:143], v[188:191], v[62:65]
	v_mfma_f32_16x16x32_bf16 v[58:61], v[148:151], v[188:191], v[58:61]
	s_barrier
	s_setprio 1
	v_mfma_f32_16x16x32_bf16 v[46:49], v[140:143], v[196:199], v[46:49]
	v_mfma_f32_16x16x32_bf16 v[42:45], v[148:151], v[196:199], v[42:45]
	v_mfma_f32_16x16x32_bf16 v[30:33], v[140:143], v[204:207], v[30:33]
	v_mfma_f32_16x16x32_bf16 v[26:29], v[148:151], v[204:207], v[26:29]
	v_mfma_f32_16x16x32_bf16 v[14:17], v[140:143], v[222:225], v[14:17]
	v_mfma_f32_16x16x32_bf16 v[10:13], v[148:151], v[222:225], v[10:13]
	v_mfma_f32_16x16x32_bf16 v[62:65], v[144:147], v[192:195], v[62:65]
	v_mfma_f32_16x16x32_bf16 v[58:61], v[152:155], v[192:195], v[58:61]
	v_mfma_f32_16x16x32_bf16 v[46:49], v[144:147], v[200:203], v[46:49]
	v_mfma_f32_16x16x32_bf16 v[42:45], v[152:155], v[200:203], v[42:45]
	v_mfma_f32_16x16x32_bf16 v[30:33], v[144:147], v[218:221], v[30:33]
	v_mfma_f32_16x16x32_bf16 v[26:29], v[152:155], v[218:221], v[26:29]
	v_mfma_f32_16x16x32_bf16 v[14:17], v[144:147], v[226:229], v[14:17]
	v_mfma_f32_16x16x32_bf16 v[10:13], v[152:155], v[226:229], v[10:13]
	s_setprio 0
	s_setprio 1
	v_mfma_f32_16x16x32_bf16 v[54:57], v[156:159], v[188:191], v[54:57]
	v_mfma_f32_16x16x32_bf16 v[50:53], v[170:173], v[188:191], v[50:53]
	v_mfma_f32_16x16x32_bf16 v[38:41], v[156:159], v[196:199], v[38:41]
	v_mfma_f32_16x16x32_bf16 v[34:37], v[170:173], v[196:199], v[34:37]
	v_mfma_f32_16x16x32_bf16 v[22:25], v[156:159], v[204:207], v[22:25]
	v_mfma_f32_16x16x32_bf16 v[18:21], v[170:173], v[204:207], v[18:21]
	v_mfma_f32_16x16x32_bf16 v[6:9], v[156:159], v[222:225], v[6:9]
	v_mfma_f32_16x16x32_bf16 v[2:5], v[170:173], v[222:225], v[2:5]
	v_mfma_f32_16x16x32_bf16 v[54:57], v[166:169], v[192:195], v[54:57]
	v_mfma_f32_16x16x32_bf16 v[50:53], v[174:177], v[192:195], v[50:53]
	v_mfma_f32_16x16x32_bf16 v[38:41], v[166:169], v[200:203], v[38:41]
	v_mfma_f32_16x16x32_bf16 v[34:37], v[174:177], v[200:203], v[34:37]
	v_mfma_f32_16x16x32_bf16 v[22:25], v[166:169], v[218:221], v[22:25]
	v_mfma_f32_16x16x32_bf16 v[18:21], v[174:177], v[218:221], v[18:21]
	v_mfma_f32_16x16x32_bf16 v[6:9], v[166:169], v[226:229], v[6:9]
	v_mfma_f32_16x16x32_bf16 v[2:5], v[174:177], v[226:229], v[2:5]
	s_setprio 0
	s_barrier
	s_add_i32 s3, 0, 0x18000
	s_add_i32 s42, 0, 0x1c000
	v_add_u32_e32 v152, s3, v163
	v_add_u32_e32 v174, s42, v163
	ds_read_b128 v[140:143], v152
	ds_read_b128 v[144:147], v152 offset:1024
	ds_read_b128 v[148:151], v152 offset:2048
	ds_read_b128 v[152:155], v152 offset:3072
	ds_read_b128 v[156:159], v174
	ds_read_b128 v[166:169], v174 offset:1024
	ds_read_b128 v[170:173], v174 offset:2048
	ds_read_b128 v[174:177], v174 offset:3072
	s_add_u32 s22, s22, 0x200000
	s_addc_u32 s23, s23, 0
	s_mov_b32 m0, s28
	v_lshl_add_u64 v[184:185], s[22:23], 0, v[134:135]
	ds_read_b128 v[188:191], v165 offset:32768
	ds_read_b128 v[192:195], v165 offset:33792
	ds_read_b128 v[196:199], v165 offset:34816
	ds_read_b128 v[200:203], v165 offset:35840
	ds_read_b128 v[204:207], v165 offset:36864
	ds_read_b128 v[218:221], v165 offset:37888
	ds_read_b128 v[222:225], v165 offset:38912
	ds_read_b128 v[226:229], v165 offset:39936
	global_load_lds_dwordx4 v[184:185], off
	v_lshl_add_u64 v[184:185], s[22:23], 0, v[132:133]
	s_mov_b32 m0, s29
	s_nop 0
	global_load_lds_dwordx4 v[184:185], off
	s_waitcnt vmcnt(8)
	s_waitcnt lgkmcnt(0)
	s_waitcnt lgkmcnt(0)
	v_mfma_f32_16x16x32_bf16 v[126:129], v[140:143], v[188:191], v[126:129]
	v_mfma_f32_16x16x32_bf16 v[122:125], v[148:151], v[188:191], v[122:125]
	s_barrier
	s_setprio 1
	v_mfma_f32_16x16x32_bf16 v[110:113], v[140:143], v[196:199], v[110:113]
	v_mfma_f32_16x16x32_bf16 v[106:109], v[148:151], v[196:199], v[106:109]
	v_mfma_f32_16x16x32_bf16 v[94:97], v[140:143], v[204:207], v[94:97]
	v_mfma_f32_16x16x32_bf16 v[90:93], v[148:151], v[204:207], v[90:93]
	v_mfma_f32_16x16x32_bf16 v[78:81], v[140:143], v[222:225], v[78:81]
	v_mfma_f32_16x16x32_bf16 v[74:77], v[148:151], v[222:225], v[74:77]
	v_mfma_f32_16x16x32_bf16 v[126:129], v[144:147], v[192:195], v[126:129]
	v_mfma_f32_16x16x32_bf16 v[122:125], v[152:155], v[192:195], v[122:125]
	v_mfma_f32_16x16x32_bf16 v[110:113], v[144:147], v[200:203], v[110:113]
	v_mfma_f32_16x16x32_bf16 v[106:109], v[152:155], v[200:203], v[106:109]
	v_mfma_f32_16x16x32_bf16 v[94:97], v[144:147], v[218:221], v[94:97]
	v_mfma_f32_16x16x32_bf16 v[90:93], v[152:155], v[218:221], v[90:93]
	v_mfma_f32_16x16x32_bf16 v[78:81], v[144:147], v[226:229], v[78:81]
	v_mfma_f32_16x16x32_bf16 v[74:77], v[152:155], v[226:229], v[74:77]
	s_setprio 0
	s_setprio 1
	v_mfma_f32_16x16x32_bf16 v[118:121], v[156:159], v[188:191], v[118:121]
	v_mfma_f32_16x16x32_bf16 v[114:117], v[170:173], v[188:191], v[114:117]
	v_mfma_f32_16x16x32_bf16 v[102:105], v[156:159], v[196:199], v[102:105]
	v_mfma_f32_16x16x32_bf16 v[98:101], v[170:173], v[196:199], v[98:101]
	v_mfma_f32_16x16x32_bf16 v[86:89], v[156:159], v[204:207], v[86:89]
	v_mfma_f32_16x16x32_bf16 v[82:85], v[170:173], v[204:207], v[82:85]
	v_mfma_f32_16x16x32_bf16 v[70:73], v[156:159], v[222:225], v[70:73]
	v_mfma_f32_16x16x32_bf16 v[66:69], v[170:173], v[222:225], v[66:69]
	v_mfma_f32_16x16x32_bf16 v[118:121], v[166:169], v[192:195], v[118:121]
	v_mfma_f32_16x16x32_bf16 v[114:117], v[174:177], v[192:195], v[114:117]
	v_mfma_f32_16x16x32_bf16 v[102:105], v[166:169], v[200:203], v[102:105]
	v_mfma_f32_16x16x32_bf16 v[98:101], v[174:177], v[200:203], v[98:101]
	v_mfma_f32_16x16x32_bf16 v[86:89], v[166:169], v[218:221], v[86:89]
	v_mfma_f32_16x16x32_bf16 v[82:85], v[174:177], v[218:221], v[82:85]
	v_mfma_f32_16x16x32_bf16 v[70:73], v[166:169], v[226:229], v[70:73]
	v_mfma_f32_16x16x32_bf16 v[66:69], v[174:177], v[226:229], v[66:69]
	s_setprio 0
	s_barrier
	s_add_i32 s3, s3, s24
	v_lshl_add_u64 v[160:161], v[160:161], 0, s[52:53]
	s_mov_b32 m0, s3
	ds_read_b128 v[188:191], v165 offset:49152
	ds_read_b128 v[192:195], v165 offset:50176
	ds_read_b128 v[196:199], v165 offset:51200
	ds_read_b128 v[200:203], v165 offset:52224
	ds_read_b128 v[204:207], v165 offset:53248
	ds_read_b128 v[218:221], v165 offset:54272
	ds_read_b128 v[222:225], v165 offset:55296
	ds_read_b128 v[226:229], v165 offset:56320
	global_load_lds_dwordx4 v[160:161], off
	s_add_i32 m0, s3, 0x2000
	s_add_u32 s20, s20, 0x200080
	v_lshl_add_u64 v[160:161], v[178:179], 0, s[52:53]
	s_addc_u32 s21, s21, 0
	s_add_i32 s3, s42, s24
	global_load_lds_dwordx4 v[160:161], off
	v_lshl_add_u64 v[160:161], s[20:21], 0, v[0:1]
	s_mov_b32 m0, s3
	s_nop 0
	global_load_lds_dwordx4 v[160:161], off
	v_lshl_add_u64 v[160:161], s[20:21], 0, v[130:131]
	s_add_i32 m0, s3, 0x2000
	s_nop 0
	global_load_lds_dwordx4 v[160:161], off
	v_lshl_add_u64 v[160:161], v[180:181], 0, s[52:53]
	s_mov_b32 m0, s30
	s_nop 0
	global_load_lds_dwordx4 v[160:161], off
	v_lshl_add_u64 v[160:161], v[182:183], 0, s[52:53]
	s_mov_b32 m0, s31
	s_nop 0
	global_load_lds_dwordx4 v[160:161], off
	s_waitcnt vmcnt(8)
	s_waitcnt lgkmcnt(0)
	s_waitcnt lgkmcnt(0)
	v_mfma_f32_16x16x32_bf16 v[62:65], v[140:143], v[188:191], v[62:65]
	v_mfma_f32_16x16x32_bf16 v[58:61], v[148:151], v[188:191], v[58:61]
	s_barrier
	s_setprio 1
	v_mfma_f32_16x16x32_bf16 v[46:49], v[140:143], v[196:199], v[46:49]
	v_mfma_f32_16x16x32_bf16 v[42:45], v[148:151], v[196:199], v[42:45]
	v_mfma_f32_16x16x32_bf16 v[30:33], v[140:143], v[204:207], v[30:33]
	v_mfma_f32_16x16x32_bf16 v[26:29], v[148:151], v[204:207], v[26:29]
	v_mfma_f32_16x16x32_bf16 v[14:17], v[140:143], v[222:225], v[14:17]
	v_mfma_f32_16x16x32_bf16 v[10:13], v[148:151], v[222:225], v[10:13]
	v_mfma_f32_16x16x32_bf16 v[62:65], v[144:147], v[192:195], v[62:65]
	v_mfma_f32_16x16x32_bf16 v[58:61], v[152:155], v[192:195], v[58:61]
	v_mfma_f32_16x16x32_bf16 v[46:49], v[144:147], v[200:203], v[46:49]
	v_mfma_f32_16x16x32_bf16 v[42:45], v[152:155], v[200:203], v[42:45]
	v_mfma_f32_16x16x32_bf16 v[30:33], v[144:147], v[218:221], v[30:33]
	v_mfma_f32_16x16x32_bf16 v[26:29], v[152:155], v[218:221], v[26:29]
	v_mfma_f32_16x16x32_bf16 v[14:17], v[144:147], v[226:229], v[14:17]
	v_mfma_f32_16x16x32_bf16 v[10:13], v[152:155], v[226:229], v[10:13]
	s_setprio 0
	s_setprio 1
	v_mfma_f32_16x16x32_bf16 v[54:57], v[156:159], v[188:191], v[54:57]
	v_mfma_f32_16x16x32_bf16 v[50:53], v[170:173], v[188:191], v[50:53]
	v_mfma_f32_16x16x32_bf16 v[38:41], v[156:159], v[196:199], v[38:41]
	v_mfma_f32_16x16x32_bf16 v[34:37], v[170:173], v[196:199], v[34:37]
	v_mfma_f32_16x16x32_bf16 v[22:25], v[156:159], v[204:207], v[22:25]
	v_mfma_f32_16x16x32_bf16 v[18:21], v[170:173], v[204:207], v[18:21]
	v_mfma_f32_16x16x32_bf16 v[6:9], v[156:159], v[222:225], v[6:9]
	v_mfma_f32_16x16x32_bf16 v[2:5], v[170:173], v[222:225], v[2:5]
	v_mfma_f32_16x16x32_bf16 v[54:57], v[166:169], v[192:195], v[54:57]
	v_mfma_f32_16x16x32_bf16 v[50:53], v[174:177], v[192:195], v[50:53]
	v_mfma_f32_16x16x32_bf16 v[38:41], v[166:169], v[200:203], v[38:41]
	v_mfma_f32_16x16x32_bf16 v[34:37], v[174:177], v[200:203], v[34:37]
	v_mfma_f32_16x16x32_bf16 v[22:25], v[166:169], v[218:221], v[22:25]
	v_mfma_f32_16x16x32_bf16 v[18:21], v[174:177], v[218:221], v[18:21]
	v_mfma_f32_16x16x32_bf16 v[6:9], v[166:169], v[226:229], v[6:9]
	v_mfma_f32_16x16x32_bf16 v[2:5], v[174:177], v[226:229], v[2:5]
	s_setprio 0
	s_barrier
	s_add_i32 s47, s47, 2
	s_add_u32 s18, s18, 0x100
	s_addc_u32 s19, s19, 0
	s_add_u32 s45, s45, 0x100
	s_addc_u32 s46, s46, 0
	s_cmpk_gt_u32 s47, 0x7d
	s_cbranch_scc0 .LBB0_1046
	s_and_b64 vcc, exec, s[8:9]
	s_movk_i32 s41, 0x6000
	s_mov_b32 s44, 0x8000
	s_mov_b32 s45, 0xa000
	s_cbranch_vccz .LBB0_1049
	s_barrier
